# score pass: first two K batches issued before the Q-load wait
# baseline (speedup 1.0000x reference)
; #define LAS __attribute__((address_space(3)))
; DI float bflo(unsigned w) { return __uint_as_float(w << 16); }
; DI float bfhi(unsigned w) { return __uint_as_float(w & 0xffff0000u); }
; DI float bf2f(bf16_t b) { return __uint_as_float((unsigned)b << 16); }
; #define LDS_WAIT() asm volatile("s_waitcnt lgkmcnt(0)" ::: "memory")
; DI void attn_sample_unit(const Params& p, int u, const bf16_t* Q, const bf16_t* Kb, const bf16_t* Vb, bf16_t* att, LAS float* sl, int lane) {
;     const int h = u & 15, t = (u >> 4) & 3, b = u >> 6;
;     const size_t qrow = (size_t)NP + b * 4 + t;
;     const float* ck = p.in[4]; const float* cv = p.in[5];
;     sl[lane] = bf2f(Q[qrow * 1024 + h * 64 + lane]);
;     LDS_WAIT();
;     float mx = -INFINITY;
; #pragma unroll 1
;     for (int e = 0; e < 9; ++e) { const int pat = e / 3, r = e - 3 * pat; const int dil = 1 << (2 * pat);
;         const int j = lane + 64 * r; const bool valid = j <= 128; const int idx = 2048 + t - dil * (valid ? j : 0);
;         float dot = 0.f;
;         if (idx >= 2048) { const bf16_t* kp = Kb + ((size_t)NP + b * 4 + (idx - 2048)) * 1024 + h * 64;
; #pragma unroll
;             for (int d8 = 0; d8 < 8; ++d8) { const u32x4 kw = *(const u32x4*)(kp + 8 * d8); const f32x4 q0 = *(const LAS f32x4*)(sl + 8 * d8), q1 = *(const LAS f32x4*)(sl + 8 * d8 + 4);
;                 dot += (bflo(kw.x) * q0[0] + bfhi(kw.x) * q0[1]) + (bflo(kw.y) * q0[2] + bfhi(kw.y) * q0[3]) + (bflo(kw.z) * q1[0] + bfhi(kw.z) * q1[1]) + (bflo(kw.w) * q1[2] + bfhi(kw.w) * q1[3]); } }
;         else { const float* kp = ck + (((size_t)b * 2048 + idx) * 16 + h) * 64;
; #pragma unroll
;             for (int d4 = 0; d4 < 16; ++d4) { const f32x4 kv = *(const f32x4*)(kp + 4 * d4); const f32x4 qv = *(const LAS f32x4*)(sl + 4 * d4); dot += (kv[0] * qv[0] + kv[1] * qv[1]) + (kv[2] * qv[2] + kv[3] * qv[3]); } }
;         if (valid) { sl[64 + pat * 192 + j] = dot; mx = fmaxf(mx, dot); } }
.LBB0_1521:
	s_ashr_i32 s86, s80, 6
	s_lshl_b32 s0, s86, 2
	s_add_i32 s0, s0, 0x8000
	s_and_b32 s4, s80, 3
	s_ashr_i32 s1, s0, 31
	s_or_b32 s76, s0, s4
	s_mov_b32 s77, s1
	s_lshl_b64 s[78:79], s[76:77], 10
	s_bfe_u32 s5, s80, 0x40002
	v_writelane_b32 v254, s78, 12
	s_lshl_b32 s2, s5, 6
	s_lshl_b64 s[76:77], s[76:77], 11
	v_writelane_b32 v254, s79, 13
	v_writelane_b32 v254, s2, 10
	s_mov_b32 s90, s82
	v_readlane_b32 s78, v254, 6
	v_readlane_b32 s79, v254, 7
	s_add_u32 s2, s78, s76
	s_addc_u32 s77, s79, s77
	s_lshl_b32 s78, s5, 7
	s_add_u32 s76, s2, s78
	s_addc_u32 s77, s77, 0
	v_lshl_add_u64 v[0:1], v[128:129], 1, s[76:77]
	global_load_ushort v0, v[0:1], off
	s_or_b32 s2, s4, 0x800
	s_add_u32 s88, s96, s78
	s_addc_u32 s89, s97, 0
	s_ashr_i32 s87, s86, 31
	s_lshl_b32 s78, s5, 8
	s_lshl_b64 s[76:77], s[86:87], 23
	v_readlane_b32 s92, v254, 14
	v_readlane_b32 s93, v254, 15
	s_add_u32 s76, s92, s76
	s_addc_u32 s77, s93, s77
	v_readlane_b32 s94, v254, 16
	s_add_u32 s84, s76, s78
	s_addc_u32 s85, s77, 0
	v_mov_b32_e32 v40, 0xff800000
	v_mov_b32_e32 v41, v128
	v_mov_b32_e32 v42, v210
	s_mov_b32 s94, 0
	v_readlane_b32 s95, v254, 17
	v_lshrrev_b32_e32 v41, 4, v128
	v_and_b32_e32 v42, 15, v128
	v_lshlrev_b32_e32 v43, 4, v42
	s_lshl_b32 s1, s0, 11
	s_add_u32 s94, s88, s1
	s_addc_u32 s95, s89, 0
	v_lshlrev_b32_e32 v102, 11, v41
	v_lshl_add_u32 v102, v42, 3, v102
	global_load_dwordx2 v[100:101], v102, s[94:95]
	v_lshlrev_b32_e32 v49, 0, v41
	v_sub_u32_e32 v49, s2, v49
	v_min_i32_e32 v50, 0x7ff, v49
	v_lshl_add_u32 v49, v49, 12, v43
	v_lshl_add_u32 v50, v50, 12, v43
	s_mov_b64 s[76:77], s[84:85]
	global_load_dwordx4 v[112:115], v50, s[76:77]
	s_sub_u32 s76, s76, 0x4000
	s_subb_u32 s77, s77, 0
	global_load_dwordx4 v[4:7], v49, s[76:77]
	s_sub_u32 s76, s76, 0x4000
	s_subb_u32 s77, s77, 0
	global_load_dwordx4 v[8:11], v49, s[76:77]
	s_sub_u32 s76, s76, 0x4000
	s_subb_u32 s77, s77, 0
	global_load_dwordx4 v[12:15], v49, s[76:77]
	s_sub_u32 s76, s76, 0x4000
	s_subb_u32 s77, s77, 0
	global_load_dwordx4 v[16:19], v49, s[76:77]
	s_sub_u32 s76, s76, 0x4000
	s_subb_u32 s77, s77, 0
	global_load_dwordx4 v[20:23], v49, s[76:77]
	s_sub_u32 s76, s76, 0x4000
	s_subb_u32 s77, s77, 0
	global_load_dwordx4 v[24:27], v49, s[76:77]
	s_sub_u32 s76, s76, 0x4000
	s_subb_u32 s77, s77, 0
	global_load_dwordx4 v[28:31], v49, s[76:77]
	s_sub_u32 s76, s76, 0x4000
	s_subb_u32 s77, s77, 0
	global_load_dwordx4 v[32:35], v49, s[76:77]
	s_sub_u32 s76, s76, 0x4000
	s_subb_u32 s77, s77, 0
	global_load_dwordx4 v[36:39], v49, s[76:77]
	s_sub_u32 s76, s76, 0x4000
	s_subb_u32 s77, s77, 0
	global_load_dwordx4 v[52:55], v49, s[76:77]
	s_sub_u32 s76, s76, 0x4000
	s_subb_u32 s77, s77, 0
	global_load_dwordx4 v[56:59], v49, s[76:77]
	s_sub_u32 s76, s76, 0x4000
	s_subb_u32 s77, s77, 0
	global_load_dwordx4 v[60:63], v49, s[76:77]
	s_sub_u32 s76, s76, 0x4000
	s_subb_u32 s77, s77, 0
	global_load_dwordx4 v[64:67], v49, s[76:77]
	s_sub_u32 s76, s76, 0x4000
	s_subb_u32 s77, s77, 0
	global_load_dwordx4 v[68:71], v49, s[76:77]
	s_sub_u32 s76, s76, 0x4000
	s_subb_u32 s77, s77, 0
	global_load_dwordx4 v[72:75], v49, s[76:77]
	s_sub_u32 s76, s76, 0x4000
	s_subb_u32 s77, s77, 0
	global_load_dwordx4 v[76:79], v49, s[76:77]
	s_sub_u32 s76, s76, 0x4000
	s_subb_u32 s77, s77, 0
	global_load_dwordx4 v[80:83], v49, s[76:77]
	s_sub_u32 s76, s76, 0x4000
	s_subb_u32 s77, s77, 0
	global_load_dwordx4 v[84:87], v49, s[76:77]
	s_sub_u32 s76, s76, 0x4000
	s_subb_u32 s77, s77, 0
	global_load_dwordx4 v[88:91], v49, s[76:77]
	s_sub_u32 s76, s76, 0x4000
	s_subb_u32 s77, s77, 0
	global_load_dwordx4 v[92:95], v49, s[76:77]
	s_sub_u32 s76, s76, 0x4000
	s_subb_u32 s77, s77, 0
	global_load_dwordx4 v[96:99], v49, s[76:77]
	s_sub_u32 s76, s76, 0x4000
	s_subb_u32 s77, s77, 0
	s_waitcnt vmcnt(23)
	v_lshlrev_b32_e32 v0, 16, v0
	ds_write_b32 v145, v0
	s_waitcnt lgkmcnt(0)
	v_add_u32_e32 v51, s3, v43
	ds_read_b128 v[44:47], v51
	v_lshlrev_b32_e32 v48, 2, v41
	v_add_u32_e32 v48, s3, v48
	v_add_u32_e32 v48, 0x100, v48
	s_mov_b32 s100, 0x10001
	s_mov_b32 s101, 0x10001
	s_sub_i32 s1, 3, s4
	s_lshl_b32 s1, s1, 4
	s_lshr_b64 s[100:101], s[100:101], s1
	s_mov_b32 s98, 0x10001
	s_mov_b32 s99, 0x10001
	s_xor_b64 s[98:99], s[98:99], s[100:101]
	s_waitcnt lgkmcnt(0)
	s_waitcnt vmcnt(11)
; #define LAS __attribute__((address_space(3)))
; DI float bflo(unsigned w) { return __uint_as_float(w << 16); }
; DI float bfhi(unsigned w) { return __uint_as_float(w & 0xffff0000u); }
; DI void attn_sample_unit(const Params& p, int u, const bf16_t* Q, const bf16_t* Kb, const bf16_t* Vb, bf16_t* att, LAS float* sl, int lane) {
;     ...
;     for (int e = 0; e < 9; ++e) { const int pat = e / 3, r = e - 3 * pat; const int dil = 1 << (2 * pat);
;         const int j = lane + 64 * r; const bool valid = j <= 128; const int idx = 2048 + t - dil * (valid ? j : 0);
;         float dot = 0.f;
;         if (idx >= 2048) { const bf16_t* kp = Kb + ((size_t)NP + b * 4 + (idx - 2048)) * 1024 + h * 64;
; #pragma unroll
;             for (int d8 = 0; d8 < 8; ++d8) { const u32x4 kw = *(const u32x4*)(kp + 8 * d8); const f32x4 q0 = *(const LAS f32x4*)(sl + 8 * d8), q1 = *(const LAS f32x4*)(sl + 8 * d8 + 4);
;                 dot += (bflo(kw.x) * q0[0] + bfhi(kw.x) * q0[1]) + (bflo(kw.y) * q0[2] + bfhi(kw.y) * q0[3]) + (bflo(kw.z) * q1[0] + bfhi(kw.z) * q1[1]) + (bflo(kw.w) * q1[2] + bfhi(kw.w) * q1[3]); } }
;         else { const float* kp = ck + (((size_t)b * 2048 + idx) * 16 + h) * 64;
; #pragma unroll
;             for (int d4 = 0; d4 < 16; ++d4) { const f32x4 kv = *(const f32x4*)(kp + 4 * d4); const f32x4 qv = *(const LAS f32x4*)(sl + 4 * d4); dot += (kv[0] * qv[0] + kv[1] * qv[1]) + (kv[2] * qv[2] + kv[3] * qv[3]); } }
;         if (valid) { sl[64 + pat * 192 + j] = dot; mx = fmaxf(mx, dot); } }
	v_lshlrev_b32_e32 v104, 16, v100
	v_and_b32_e32 v105, 0xffff0000, v100
	v_lshlrev_b32_e32 v106, 16, v101
	v_and_b32_e32 v107, 0xffff0000, v101
	v_mul_f32_e32 v104, v104, v44
	v_fmac_f32_e32 v104, v105, v45
	v_fmac_f32_e32 v104, v106, v46
	v_fmac_f32_e32 v104, v107, v47
	s_nop 1
	v_add_f32_dpp v104, v104, v104 quad_perm:[1,0,3,2] row_mask:0xf bank_mask:0xf
	s_nop 1
	v_add_f32_dpp v104, v104, v104 quad_perm:[2,3,0,1] row_mask:0xf bank_mask:0xf
	s_nop 1
	v_add_f32_dpp v104, v104, v104 row_half_mirror row_mask:0xf bank_mask:0xf
	s_nop 1
	v_add_f32_dpp v104, v104, v104 row_mirror row_mask:0xf bank_mask:0xf
	s_lshl_b32 s1, s4, 2
	s_add_i32 s1, s1, s3
	s_addk_i32 s1, 0x100
	v_lshlrev_b32_e32 v108, 2, v41
	v_sub_u32_e32 v108, s1, v108
	v_mov_b32_e32 v109, s3
	s_mov_b64 exec, s[100:101]
	ds_write_b32 v108, v104
	v_max_f32_e32 v40, v40, v104
	s_lshl_b32 s1, s4, 4
	s_lshl_b64 s[82:83], 1, s1
	s_mov_b64 exec, s[82:83]
	ds_write_b32 v109, v104 offset:1024
	ds_write_b32 v109, v104 offset:1792
	s_mov_b64 exec, -1
	s_nop 4
	v_mul_f32_e32 v112, v112, v44
	v_mul_f32_e32 v4, v4, v44
	v_mul_f32_e32 v8, v8, v44
	v_mul_f32_e32 v12, v12, v44
	v_mul_f32_e32 v16, v16, v44
	v_mul_f32_e32 v20, v20, v44
	v_mul_f32_e32 v24, v24, v44
	v_mul_f32_e32 v28, v28, v44
	v_mul_f32_e32 v32, v32, v44
	v_mul_f32_e32 v36, v36, v44
	v_mul_f32_e32 v52, v52, v44
	v_fmac_f32_e32 v112, v113, v45
	v_fmac_f32_e32 v4, v5, v45
	v_fmac_f32_e32 v8, v9, v45
	v_fmac_f32_e32 v12, v13, v45
	v_fmac_f32_e32 v16, v17, v45
	v_fmac_f32_e32 v20, v21, v45
	v_fmac_f32_e32 v24, v25, v45
	v_fmac_f32_e32 v28, v29, v45
	v_fmac_f32_e32 v32, v33, v45
	v_fmac_f32_e32 v36, v37, v45
	v_fmac_f32_e32 v52, v53, v45
	v_fmac_f32_e32 v112, v114, v46
	v_fmac_f32_e32 v4, v6, v46
	v_fmac_f32_e32 v8, v10, v46
	v_fmac_f32_e32 v12, v14, v46
	v_fmac_f32_e32 v16, v18, v46
	v_fmac_f32_e32 v20, v22, v46
	v_fmac_f32_e32 v24, v26, v46
	v_fmac_f32_e32 v28, v30, v46
	v_fmac_f32_e32 v32, v34, v46
	v_fmac_f32_e32 v36, v38, v46
	v_fmac_f32_e32 v52, v54, v46
	v_fmac_f32_e32 v112, v115, v47
	v_fmac_f32_e32 v4, v7, v47
	v_fmac_f32_e32 v8, v11, v47
	v_fmac_f32_e32 v12, v15, v47
	v_fmac_f32_e32 v16, v19, v47
	v_fmac_f32_e32 v20, v23, v47
	v_fmac_f32_e32 v24, v27, v47
	v_fmac_f32_e32 v28, v31, v47
	v_fmac_f32_e32 v32, v35, v47
	v_fmac_f32_e32 v36, v39, v47
	v_fmac_f32_e32 v52, v55, v47
	s_nop 1
	v_add_f32_dpp v112, v112, v112 quad_perm:[1,0,3,2] row_mask:0xf bank_mask:0xf
	v_add_f32_dpp v4, v4, v4 quad_perm:[1,0,3,2] row_mask:0xf bank_mask:0xf
	v_add_f32_dpp v8, v8, v8 quad_perm:[1,0,3,2] row_mask:0xf bank_mask:0xf
	v_add_f32_dpp v12, v12, v12 quad_perm:[1,0,3,2] row_mask:0xf bank_mask:0xf
	v_add_f32_dpp v16, v16, v16 quad_perm:[1,0,3,2] row_mask:0xf bank_mask:0xf
	v_add_f32_dpp v20, v20, v20 quad_perm:[1,0,3,2] row_mask:0xf bank_mask:0xf
	v_add_f32_dpp v24, v24, v24 quad_perm:[1,0,3,2] row_mask:0xf bank_mask:0xf
	v_add_f32_dpp v28, v28, v28 quad_perm:[1,0,3,2] row_mask:0xf bank_mask:0xf
	v_add_f32_dpp v32, v32, v32 quad_perm:[1,0,3,2] row_mask:0xf bank_mask:0xf
	v_add_f32_dpp v36, v36, v36 quad_perm:[1,0,3,2] row_mask:0xf bank_mask:0xf
	v_add_f32_dpp v52, v52, v52 quad_perm:[1,0,3,2] row_mask:0xf bank_mask:0xf
	s_nop 1
	v_add_f32_dpp v112, v112, v112 quad_perm:[2,3,0,1] row_mask:0xf bank_mask:0xf
	v_add_f32_dpp v4, v4, v4 quad_perm:[2,3,0,1] row_mask:0xf bank_mask:0xf
	v_add_f32_dpp v8, v8, v8 quad_perm:[2,3,0,1] row_mask:0xf bank_mask:0xf
	v_add_f32_dpp v12, v12, v12 quad_perm:[2,3,0,1] row_mask:0xf bank_mask:0xf
	v_add_f32_dpp v16, v16, v16 quad_perm:[2,3,0,1] row_mask:0xf bank_mask:0xf
	v_add_f32_dpp v20, v20, v20 quad_perm:[2,3,0,1] row_mask:0xf bank_mask:0xf
	v_add_f32_dpp v24, v24, v24 quad_perm:[2,3,0,1] row_mask:0xf bank_mask:0xf
	v_add_f32_dpp v28, v28, v28 quad_perm:[2,3,0,1] row_mask:0xf bank_mask:0xf
	v_add_f32_dpp v32, v32, v32 quad_perm:[2,3,0,1] row_mask:0xf bank_mask:0xf
	v_add_f32_dpp v36, v36, v36 quad_perm:[2,3,0,1] row_mask:0xf bank_mask:0xf
	v_add_f32_dpp v52, v52, v52 quad_perm:[2,3,0,1] row_mask:0xf bank_mask:0xf
	s_nop 1
	v_add_f32_dpp v112, v112, v112 row_half_mirror row_mask:0xf bank_mask:0xf
	v_add_f32_dpp v4, v4, v4 row_half_mirror row_mask:0xf bank_mask:0xf
	v_add_f32_dpp v8, v8, v8 row_half_mirror row_mask:0xf bank_mask:0xf
	v_add_f32_dpp v12, v12, v12 row_half_mirror row_mask:0xf bank_mask:0xf
	v_add_f32_dpp v16, v16, v16 row_half_mirror row_mask:0xf bank_mask:0xf
	v_add_f32_dpp v20, v20, v20 row_half_mirror row_mask:0xf bank_mask:0xf
	v_add_f32_dpp v24, v24, v24 row_half_mirror row_mask:0xf bank_mask:0xf
	v_add_f32_dpp v28, v28, v28 row_half_mirror row_mask:0xf bank_mask:0xf
	v_add_f32_dpp v32, v32, v32 row_half_mirror row_mask:0xf bank_mask:0xf
	v_add_f32_dpp v36, v36, v36 row_half_mirror row_mask:0xf bank_mask:0xf
	v_add_f32_dpp v52, v52, v52 row_half_mirror row_mask:0xf bank_mask:0xf
	s_nop 1
	v_add_f32_dpp v112, v112, v112 row_mirror row_mask:0xf bank_mask:0xf
	v_add_f32_dpp v4, v4, v4 row_mirror row_mask:0xf bank_mask:0xf
	v_add_f32_dpp v8, v8, v8 row_mirror row_mask:0xf bank_mask:0xf
	v_add_f32_dpp v12, v12, v12 row_mirror row_mask:0xf bank_mask:0xf
	v_add_f32_dpp v16, v16, v16 row_mirror row_mask:0xf bank_mask:0xf
	v_add_f32_dpp v20, v20, v20 row_mirror row_mask:0xf bank_mask:0xf
	v_add_f32_dpp v24, v24, v24 row_mirror row_mask:0xf bank_mask:0xf
	v_add_f32_dpp v28, v28, v28 row_mirror row_mask:0xf bank_mask:0xf
	v_add_f32_dpp v32, v32, v32 row_mirror row_mask:0xf bank_mask:0xf
	v_add_f32_dpp v36, v36, v36 row_mirror row_mask:0xf bank_mask:0xf
	v_add_f32_dpp v52, v52, v52 row_mirror row_mask:0xf bank_mask:0xf
	s_nop 1
	s_mov_b64 exec, s[98:99]
	ds_write_b32 v48, v112 offset:0
	v_max_f32_e32 v40, v40, v112
; #define LAS __attribute__((address_space(3)))
; DI float bflo(unsigned w) { return __uint_as_float(w << 16); }
; DI float bfhi(unsigned w) { return __uint_as_float(w & 0xffff0000u); }
; DI void attn_sample_unit(const Params& p, int u, const bf16_t* Q, const bf16_t* Kb, const bf16_t* Vb, bf16_t* att, LAS float* sl, int lane) {
;     ...
;     for (int e = 0; e < 9; ++e) { const int pat = e / 3, r = e - 3 * pat; const int dil = 1 << (2 * pat);
;         const int j = lane + 64 * r; const bool valid = j <= 128; const int idx = 2048 + t - dil * (valid ? j : 0);
;         float dot = 0.f;
;         if (idx >= 2048) { const bf16_t* kp = Kb + ((size_t)NP + b * 4 + (idx - 2048)) * 1024 + h * 64;
; #pragma unroll
;             for (int d8 = 0; d8 < 8; ++d8) { const u32x4 kw = *(const u32x4*)(kp + 8 * d8); const f32x4 q0 = *(const LAS f32x4*)(sl + 8 * d8), q1 = *(const LAS f32x4*)(sl + 8 * d8 + 4);
;                 dot += (bflo(kw.x) * q0[0] + bfhi(kw.x) * q0[1]) + (bflo(kw.y) * q0[2] + bfhi(kw.y) * q0[3]) + (bflo(kw.z) * q1[0] + bfhi(kw.z) * q1[1]) + (bflo(kw.w) * q1[2] + bfhi(kw.w) * q1[3]); } }
;         else { const float* kp = ck + (((size_t)b * 2048 + idx) * 16 + h) * 64;
; #pragma unroll
;             for (int d4 = 0; d4 < 16; ++d4) { const f32x4 kv = *(const f32x4*)(kp + 4 * d4); const f32x4 qv = *(const LAS f32x4*)(sl + 4 * d4); dot += (kv[0] * qv[0] + kv[1] * qv[1]) + (kv[2] * qv[2] + kv[3] * qv[3]); } }
;         if (valid) { sl[64 + pat * 192 + j] = dot; mx = fmaxf(mx, dot); } }
	s_mov_b32 s82, 0x10001
	s_mov_b32 s83, 0x10001
	s_mov_b64 exec, s[82:83]
	ds_write_b32 v48, v4 offset:16
	v_max_f32_e32 v40, v40, v4
	ds_write_b32 v48, v8 offset:32
	v_max_f32_e32 v40, v40, v8
	ds_write_b32 v48, v12 offset:48
	v_max_f32_e32 v40, v40, v12
	ds_write_b32 v48, v16 offset:64
	v_max_f32_e32 v40, v40, v16
	ds_write_b32 v48, v20 offset:80
	v_max_f32_e32 v40, v40, v20
	ds_write_b32 v48, v24 offset:96
	v_max_f32_e32 v40, v40, v24
	ds_write_b32 v48, v28 offset:112
	v_max_f32_e32 v40, v40, v28
	ds_write_b32 v48, v32 offset:128
	v_max_f32_e32 v40, v40, v32
	ds_write_b32 v48, v36 offset:144
	v_max_f32_e32 v40, v40, v36
	ds_write_b32 v48, v52 offset:160
	v_max_f32_e32 v40, v40, v52
	s_mov_b64 exec, -1
	s_nop 4
	global_load_dwordx4 v[112:115], v49, s[76:77]
	s_sub_u32 s76, s76, 0x4000
	s_subb_u32 s77, s77, 0
	global_load_dwordx4 v[4:7], v49, s[76:77]
	s_sub_u32 s76, s76, 0x4000
	s_subb_u32 s77, s77, 0
	global_load_dwordx4 v[8:11], v49, s[76:77]
	s_sub_u32 s76, s76, 0x4000
	s_subb_u32 s77, s77, 0
	global_load_dwordx4 v[12:15], v49, s[76:77]
	s_sub_u32 s76, s76, 0x4000
	s_subb_u32 s77, s77, 0
	global_load_dwordx4 v[16:19], v49, s[76:77]
	s_sub_u32 s76, s76, 0x4000
	s_subb_u32 s77, s77, 0
	global_load_dwordx4 v[20:23], v49, s[76:77]
	s_sub_u32 s76, s76, 0x4000
	s_subb_u32 s77, s77, 0
	global_load_dwordx4 v[24:27], v49, s[76:77]
	s_sub_u32 s76, s76, 0x4000
	s_subb_u32 s77, s77, 0
	global_load_dwordx4 v[28:31], v49, s[76:77]
	s_sub_u32 s76, s76, 0x4000
	s_subb_u32 s77, s77, 0
	global_load_dwordx4 v[32:35], v49, s[76:77]
	s_sub_u32 s76, s76, 0x4000
	s_subb_u32 s77, s77, 0
	global_load_dwordx4 v[36:39], v49, s[76:77]
	s_sub_u32 s76, s76, 0x4000
	s_subb_u32 s77, s77, 0
	s_mov_b64 exec, 0xffff
	global_load_dwordx4 v[52:55], v49, s[76:77]
	s_mov_b64 exec, -1
	s_waitcnt vmcnt(11)
	v_mul_f32_e32 v56, v56, v44
	v_mul_f32_e32 v60, v60, v44
	v_mul_f32_e32 v64, v64, v44
	v_mul_f32_e32 v68, v68, v44
	v_mul_f32_e32 v72, v72, v44
	v_mul_f32_e32 v76, v76, v44
	v_mul_f32_e32 v80, v80, v44
	v_mul_f32_e32 v84, v84, v44
	v_mul_f32_e32 v88, v88, v44
	v_mul_f32_e32 v92, v92, v44
	v_mul_f32_e32 v96, v96, v44
	v_fmac_f32_e32 v56, v57, v45
	v_fmac_f32_e32 v60, v61, v45
	v_fmac_f32_e32 v64, v65, v45
	v_fmac_f32_e32 v68, v69, v45
	v_fmac_f32_e32 v72, v73, v45
	v_fmac_f32_e32 v76, v77, v45
	v_fmac_f32_e32 v80, v81, v45
	v_fmac_f32_e32 v84, v85, v45
	v_fmac_f32_e32 v88, v89, v45
	v_fmac_f32_e32 v92, v93, v45
	v_fmac_f32_e32 v96, v97, v45
	v_fmac_f32_e32 v56, v58, v46
	v_fmac_f32_e32 v60, v62, v46
	v_fmac_f32_e32 v64, v66, v46
	v_fmac_f32_e32 v68, v70, v46
	v_fmac_f32_e32 v72, v74, v46
	v_fmac_f32_e32 v76, v78, v46
	v_fmac_f32_e32 v80, v82, v46
	v_fmac_f32_e32 v84, v86, v46
	v_fmac_f32_e32 v88, v90, v46
	v_fmac_f32_e32 v92, v94, v46
	v_fmac_f32_e32 v96, v98, v46
	v_fmac_f32_e32 v56, v59, v47
	v_fmac_f32_e32 v60, v63, v47
	v_fmac_f32_e32 v64, v67, v47
	v_fmac_f32_e32 v68, v71, v47
	v_fmac_f32_e32 v72, v75, v47
	v_fmac_f32_e32 v76, v79, v47
	v_fmac_f32_e32 v80, v83, v47
	v_fmac_f32_e32 v84, v87, v47
	v_fmac_f32_e32 v88, v91, v47
	v_fmac_f32_e32 v92, v95, v47
	v_fmac_f32_e32 v96, v99, v47
	s_nop 1
	v_add_f32_dpp v56, v56, v56 quad_perm:[1,0,3,2] row_mask:0xf bank_mask:0xf
	v_add_f32_dpp v60, v60, v60 quad_perm:[1,0,3,2] row_mask:0xf bank_mask:0xf
	v_add_f32_dpp v64, v64, v64 quad_perm:[1,0,3,2] row_mask:0xf bank_mask:0xf
	v_add_f32_dpp v68, v68, v68 quad_perm:[1,0,3,2] row_mask:0xf bank_mask:0xf
	v_add_f32_dpp v72, v72, v72 quad_perm:[1,0,3,2] row_mask:0xf bank_mask:0xf
	v_add_f32_dpp v76, v76, v76 quad_perm:[1,0,3,2] row_mask:0xf bank_mask:0xf
	v_add_f32_dpp v80, v80, v80 quad_perm:[1,0,3,2] row_mask:0xf bank_mask:0xf
	v_add_f32_dpp v84, v84, v84 quad_perm:[1,0,3,2] row_mask:0xf bank_mask:0xf
	v_add_f32_dpp v88, v88, v88 quad_perm:[1,0,3,2] row_mask:0xf bank_mask:0xf
	v_add_f32_dpp v92, v92, v92 quad_perm:[1,0,3,2] row_mask:0xf bank_mask:0xf
	v_add_f32_dpp v96, v96, v96 quad_perm:[1,0,3,2] row_mask:0xf bank_mask:0xf
	s_nop 1
	v_add_f32_dpp v56, v56, v56 quad_perm:[2,3,0,1] row_mask:0xf bank_mask:0xf
	v_add_f32_dpp v60, v60, v60 quad_perm:[2,3,0,1] row_mask:0xf bank_mask:0xf
	v_add_f32_dpp v64, v64, v64 quad_perm:[2,3,0,1] row_mask:0xf bank_mask:0xf
	v_add_f32_dpp v68, v68, v68 quad_perm:[2,3,0,1] row_mask:0xf bank_mask:0xf
	v_add_f32_dpp v72, v72, v72 quad_perm:[2,3,0,1] row_mask:0xf bank_mask:0xf
	v_add_f32_dpp v76, v76, v76 quad_perm:[2,3,0,1] row_mask:0xf bank_mask:0xf
	v_add_f32_dpp v80, v80, v80 quad_perm:[2,3,0,1] row_mask:0xf bank_mask:0xf
	v_add_f32_dpp v84, v84, v84 quad_perm:[2,3,0,1] row_mask:0xf bank_mask:0xf
	v_add_f32_dpp v88, v88, v88 quad_perm:[2,3,0,1] row_mask:0xf bank_mask:0xf
	v_add_f32_dpp v92, v92, v92 quad_perm:[2,3,0,1] row_mask:0xf bank_mask:0xf
	v_add_f32_dpp v96, v96, v96 quad_perm:[2,3,0,1] row_mask:0xf bank_mask:0xf
	s_nop 1
	v_add_f32_dpp v56, v56, v56 row_half_mirror row_mask:0xf bank_mask:0xf
	v_add_f32_dpp v60, v60, v60 row_half_mirror row_mask:0xf bank_mask:0xf
	v_add_f32_dpp v64, v64, v64 row_half_mirror row_mask:0xf bank_mask:0xf
	v_add_f32_dpp v68, v68, v68 row_half_mirror row_mask:0xf bank_mask:0xf
	v_add_f32_dpp v72, v72, v72 row_half_mirror row_mask:0xf bank_mask:0xf
	v_add_f32_dpp v76, v76, v76 row_half_mirror row_mask:0xf bank_mask:0xf
	v_add_f32_dpp v80, v80, v80 row_half_mirror row_mask:0xf bank_mask:0xf
	v_add_f32_dpp v84, v84, v84 row_half_mirror row_mask:0xf bank_mask:0xf
	v_add_f32_dpp v88, v88, v88 row_half_mirror row_mask:0xf bank_mask:0xf
	v_add_f32_dpp v92, v92, v92 row_half_mirror row_mask:0xf bank_mask:0xf
	v_add_f32_dpp v96, v96, v96 row_half_mirror row_mask:0xf bank_mask:0xf
	s_nop 1
; #define LAS __attribute__((address_space(3)))
; DI float bflo(unsigned w) { return __uint_as_float(w << 16); }
; DI float bfhi(unsigned w) { return __uint_as_float(w & 0xffff0000u); }
; DI void attn_sample_unit(const Params& p, int u, const bf16_t* Q, const bf16_t* Kb, const bf16_t* Vb, bf16_t* att, LAS float* sl, int lane) {
;     ...
;     for (int e = 0; e < 9; ++e) { const int pat = e / 3, r = e - 3 * pat; const int dil = 1 << (2 * pat);
;         const int j = lane + 64 * r; const bool valid = j <= 128; const int idx = 2048 + t - dil * (valid ? j : 0);
;         float dot = 0.f;
;         if (idx >= 2048) { const bf16_t* kp = Kb + ((size_t)NP + b * 4 + (idx - 2048)) * 1024 + h * 64;
; #pragma unroll
;             for (int d8 = 0; d8 < 8; ++d8) { const u32x4 kw = *(const u32x4*)(kp + 8 * d8); const f32x4 q0 = *(const LAS f32x4*)(sl + 8 * d8), q1 = *(const LAS f32x4*)(sl + 8 * d8 + 4);
;                 dot += (bflo(kw.x) * q0[0] + bfhi(kw.x) * q0[1]) + (bflo(kw.y) * q0[2] + bfhi(kw.y) * q0[3]) + (bflo(kw.z) * q1[0] + bfhi(kw.z) * q1[1]) + (bflo(kw.w) * q1[2] + bfhi(kw.w) * q1[3]); } }
;         else { const float* kp = ck + (((size_t)b * 2048 + idx) * 16 + h) * 64;
; #pragma unroll
;             for (int d4 = 0; d4 < 16; ++d4) { const f32x4 kv = *(const f32x4*)(kp + 4 * d4); const f32x4 qv = *(const LAS f32x4*)(sl + 4 * d4); dot += (kv[0] * qv[0] + kv[1] * qv[1]) + (kv[2] * qv[2] + kv[3] * qv[3]); } }
;         if (valid) { sl[64 + pat * 192 + j] = dot; mx = fmaxf(mx, dot); } }
	v_add_f32_dpp v56, v56, v56 row_mirror row_mask:0xf bank_mask:0xf
	v_add_f32_dpp v60, v60, v60 row_mirror row_mask:0xf bank_mask:0xf
	v_add_f32_dpp v64, v64, v64 row_mirror row_mask:0xf bank_mask:0xf
	v_add_f32_dpp v68, v68, v68 row_mirror row_mask:0xf bank_mask:0xf
	v_add_f32_dpp v72, v72, v72 row_mirror row_mask:0xf bank_mask:0xf
	v_add_f32_dpp v76, v76, v76 row_mirror row_mask:0xf bank_mask:0xf
	v_add_f32_dpp v80, v80, v80 row_mirror row_mask:0xf bank_mask:0xf
	v_add_f32_dpp v84, v84, v84 row_mirror row_mask:0xf bank_mask:0xf
	v_add_f32_dpp v88, v88, v88 row_mirror row_mask:0xf bank_mask:0xf
	v_add_f32_dpp v92, v92, v92 row_mirror row_mask:0xf bank_mask:0xf
	v_add_f32_dpp v96, v96, v96 row_mirror row_mask:0xf bank_mask:0xf
	s_nop 1
	s_mov_b32 s82, 0x10001
	s_mov_b32 s83, 0x10001
	s_mov_b64 exec, s[82:83]
	ds_write_b32 v48, v56 offset:176
	v_max_f32_e32 v40, v40, v56
	ds_write_b32 v48, v60 offset:192
	v_max_f32_e32 v40, v40, v60
	ds_write_b32 v48, v64 offset:208
	v_max_f32_e32 v40, v40, v64
	ds_write_b32 v48, v68 offset:224
	v_max_f32_e32 v40, v40, v68
	ds_write_b32 v48, v72 offset:240
	v_max_f32_e32 v40, v40, v72
	ds_write_b32 v48, v76 offset:256
	v_max_f32_e32 v40, v40, v76
	ds_write_b32 v48, v80 offset:272
	v_max_f32_e32 v40, v40, v80
	ds_write_b32 v48, v84 offset:288
	v_max_f32_e32 v40, v40, v84
	ds_write_b32 v48, v88 offset:304
	v_max_f32_e32 v40, v40, v88
	ds_write_b32 v48, v92 offset:320
	v_max_f32_e32 v40, v40, v92
	ds_write_b32 v48, v96 offset:336
	v_max_f32_e32 v40, v40, v96
	s_mov_b64 exec, -1
	s_nop 4
	v_lshlrev_b32_e32 v49, 2, v41
	v_sub_u32_e32 v49, s2, v49
	v_min_i32_e32 v50, 0x7ff, v49
	v_lshl_add_u32 v49, v49, 12, v43
	v_lshl_add_u32 v50, v50, 12, v43
	s_mov_b64 s[76:77], s[84:85]
	global_load_dwordx4 v[56:59], v50, s[76:77]
	s_sub_u32 s76, s76, 0x10000
	s_subb_u32 s77, s77, 0
	global_load_dwordx4 v[60:63], v49, s[76:77]
	s_sub_u32 s76, s76, 0x10000
	s_subb_u32 s77, s77, 0
	global_load_dwordx4 v[64:67], v49, s[76:77]
	s_sub_u32 s76, s76, 0x10000
	s_subb_u32 s77, s77, 0
	global_load_dwordx4 v[68:71], v49, s[76:77]
	s_sub_u32 s76, s76, 0x10000
	s_subb_u32 s77, s77, 0
	global_load_dwordx4 v[72:75], v49, s[76:77]
	s_sub_u32 s76, s76, 0x10000
	s_subb_u32 s77, s77, 0
	global_load_dwordx4 v[76:79], v49, s[76:77]
	s_sub_u32 s76, s76, 0x10000
	s_subb_u32 s77, s77, 0
	global_load_dwordx4 v[80:83], v49, s[76:77]
	s_sub_u32 s76, s76, 0x10000
	s_subb_u32 s77, s77, 0
	global_load_dwordx4 v[84:87], v49, s[76:77]
	s_sub_u32 s76, s76, 0x10000
	s_subb_u32 s77, s77, 0
	global_load_dwordx4 v[88:91], v49, s[76:77]
	s_sub_u32 s76, s76, 0x10000
	s_subb_u32 s77, s77, 0
	global_load_dwordx4 v[92:95], v49, s[76:77]
	s_sub_u32 s76, s76, 0x10000
	s_subb_u32 s77, s77, 0
	global_load_dwordx4 v[96:99], v49, s[76:77]
	s_sub_u32 s76, s76, 0x10000
	s_subb_u32 s77, s77, 0
	s_waitcnt vmcnt(11)
	v_mul_f32_e32 v112, v112, v44
	v_mul_f32_e32 v4, v4, v44
	v_mul_f32_e32 v8, v8, v44
	v_mul_f32_e32 v12, v12, v44
	v_mul_f32_e32 v16, v16, v44
	v_mul_f32_e32 v20, v20, v44
	v_mul_f32_e32 v24, v24, v44
	v_mul_f32_e32 v28, v28, v44
	v_mul_f32_e32 v32, v32, v44
	v_mul_f32_e32 v36, v36, v44
	v_mul_f32_e32 v52, v52, v44
	v_fmac_f32_e32 v112, v113, v45
	v_fmac_f32_e32 v4, v5, v45
	v_fmac_f32_e32 v8, v9, v45
	v_fmac_f32_e32 v12, v13, v45
	v_fmac_f32_e32 v16, v17, v45
	v_fmac_f32_e32 v20, v21, v45
	v_fmac_f32_e32 v24, v25, v45
	v_fmac_f32_e32 v28, v29, v45
	v_fmac_f32_e32 v32, v33, v45
	v_fmac_f32_e32 v36, v37, v45
	v_fmac_f32_e32 v52, v53, v45
	v_fmac_f32_e32 v112, v114, v46
	v_fmac_f32_e32 v4, v6, v46
	v_fmac_f32_e32 v8, v10, v46
	v_fmac_f32_e32 v12, v14, v46
	v_fmac_f32_e32 v16, v18, v46
	v_fmac_f32_e32 v20, v22, v46
	v_fmac_f32_e32 v24, v26, v46
	v_fmac_f32_e32 v28, v30, v46
	v_fmac_f32_e32 v32, v34, v46
	v_fmac_f32_e32 v36, v38, v46
	v_fmac_f32_e32 v52, v54, v46
	v_fmac_f32_e32 v112, v115, v47
	v_fmac_f32_e32 v4, v7, v47
	v_fmac_f32_e32 v8, v11, v47
	v_fmac_f32_e32 v12, v15, v47
	v_fmac_f32_e32 v16, v19, v47
	v_fmac_f32_e32 v20, v23, v47
	v_fmac_f32_e32 v24, v27, v47
	v_fmac_f32_e32 v28, v31, v47
	v_fmac_f32_e32 v32, v35, v47
	v_fmac_f32_e32 v36, v39, v47
	v_fmac_f32_e32 v52, v55, v47
	s_nop 1
	v_add_f32_dpp v112, v112, v112 quad_perm:[1,0,3,2] row_mask:0xf bank_mask:0xf
	v_add_f32_dpp v4, v4, v4 quad_perm:[1,0,3,2] row_mask:0xf bank_mask:0xf
	v_add_f32_dpp v8, v8, v8 quad_perm:[1,0,3,2] row_mask:0xf bank_mask:0xf
	v_add_f32_dpp v12, v12, v12 quad_perm:[1,0,3,2] row_mask:0xf bank_mask:0xf
	v_add_f32_dpp v16, v16, v16 quad_perm:[1,0,3,2] row_mask:0xf bank_mask:0xf
	v_add_f32_dpp v20, v20, v20 quad_perm:[1,0,3,2] row_mask:0xf bank_mask:0xf
	v_add_f32_dpp v24, v24, v24 quad_perm:[1,0,3,2] row_mask:0xf bank_mask:0xf
	v_add_f32_dpp v28, v28, v28 quad_perm:[1,0,3,2] row_mask:0xf bank_mask:0xf
	v_add_f32_dpp v32, v32, v32 quad_perm:[1,0,3,2] row_mask:0xf bank_mask:0xf
	v_add_f32_dpp v36, v36, v36 quad_perm:[1,0,3,2] row_mask:0xf bank_mask:0xf
	v_add_f32_dpp v52, v52, v52 quad_perm:[1,0,3,2] row_mask:0xf bank_mask:0xf
	s_nop 1
	v_add_f32_dpp v112, v112, v112 quad_perm:[2,3,0,1] row_mask:0xf bank_mask:0xf
	v_add_f32_dpp v4, v4, v4 quad_perm:[2,3,0,1] row_mask:0xf bank_mask:0xf
	v_add_f32_dpp v8, v8, v8 quad_perm:[2,3,0,1] row_mask:0xf bank_mask:0xf
	v_add_f32_dpp v12, v12, v12 quad_perm:[2,3,0,1] row_mask:0xf bank_mask:0xf
	v_add_f32_dpp v16, v16, v16 quad_perm:[2,3,0,1] row_mask:0xf bank_mask:0xf
	v_add_f32_dpp v20, v20, v20 quad_perm:[2,3,0,1] row_mask:0xf bank_mask:0xf
	v_add_f32_dpp v24, v24, v24 quad_perm:[2,3,0,1] row_mask:0xf bank_mask:0xf
	v_add_f32_dpp v28, v28, v28 quad_perm:[2,3,0,1] row_mask:0xf bank_mask:0xf
	v_add_f32_dpp v32, v32, v32 quad_perm:[2,3,0,1] row_mask:0xf bank_mask:0xf
; #define LAS __attribute__((address_space(3)))
; DI float bflo(unsigned w) { return __uint_as_float(w << 16); }
; DI float bfhi(unsigned w) { return __uint_as_float(w & 0xffff0000u); }
; DI void attn_sample_unit(const Params& p, int u, const bf16_t* Q, const bf16_t* Kb, const bf16_t* Vb, bf16_t* att, LAS float* sl, int lane) {
;     ...
;     for (int e = 0; e < 9; ++e) { const int pat = e / 3, r = e - 3 * pat; const int dil = 1 << (2 * pat);
;         const int j = lane + 64 * r; const bool valid = j <= 128; const int idx = 2048 + t - dil * (valid ? j : 0);
;         float dot = 0.f;
;         if (idx >= 2048) { const bf16_t* kp = Kb + ((size_t)NP + b * 4 + (idx - 2048)) * 1024 + h * 64;
; #pragma unroll
;             for (int d8 = 0; d8 < 8; ++d8) { const u32x4 kw = *(const u32x4*)(kp + 8 * d8); const f32x4 q0 = *(const LAS f32x4*)(sl + 8 * d8), q1 = *(const LAS f32x4*)(sl + 8 * d8 + 4);
;                 dot += (bflo(kw.x) * q0[0] + bfhi(kw.x) * q0[1]) + (bflo(kw.y) * q0[2] + bfhi(kw.y) * q0[3]) + (bflo(kw.z) * q1[0] + bfhi(kw.z) * q1[1]) + (bflo(kw.w) * q1[2] + bfhi(kw.w) * q1[3]); } }
;         else { const float* kp = ck + (((size_t)b * 2048 + idx) * 16 + h) * 64;
; #pragma unroll
;             for (int d4 = 0; d4 < 16; ++d4) { const f32x4 kv = *(const f32x4*)(kp + 4 * d4); const f32x4 qv = *(const LAS f32x4*)(sl + 4 * d4); dot += (kv[0] * qv[0] + kv[1] * qv[1]) + (kv[2] * qv[2] + kv[3] * qv[3]); } }
;         if (valid) { sl[64 + pat * 192 + j] = dot; mx = fmaxf(mx, dot); } }
	v_add_f32_dpp v36, v36, v36 quad_perm:[2,3,0,1] row_mask:0xf bank_mask:0xf
	v_add_f32_dpp v52, v52, v52 quad_perm:[2,3,0,1] row_mask:0xf bank_mask:0xf
	s_nop 1
	v_add_f32_dpp v112, v112, v112 row_half_mirror row_mask:0xf bank_mask:0xf
	v_add_f32_dpp v4, v4, v4 row_half_mirror row_mask:0xf bank_mask:0xf
	v_add_f32_dpp v8, v8, v8 row_half_mirror row_mask:0xf bank_mask:0xf
	v_add_f32_dpp v12, v12, v12 row_half_mirror row_mask:0xf bank_mask:0xf
	v_add_f32_dpp v16, v16, v16 row_half_mirror row_mask:0xf bank_mask:0xf
	v_add_f32_dpp v20, v20, v20 row_half_mirror row_mask:0xf bank_mask:0xf
	v_add_f32_dpp v24, v24, v24 row_half_mirror row_mask:0xf bank_mask:0xf
	v_add_f32_dpp v28, v28, v28 row_half_mirror row_mask:0xf bank_mask:0xf
	v_add_f32_dpp v32, v32, v32 row_half_mirror row_mask:0xf bank_mask:0xf
	v_add_f32_dpp v36, v36, v36 row_half_mirror row_mask:0xf bank_mask:0xf
	v_add_f32_dpp v52, v52, v52 row_half_mirror row_mask:0xf bank_mask:0xf
	s_nop 1
	v_add_f32_dpp v112, v112, v112 row_mirror row_mask:0xf bank_mask:0xf
	v_add_f32_dpp v4, v4, v4 row_mirror row_mask:0xf bank_mask:0xf
	v_add_f32_dpp v8, v8, v8 row_mirror row_mask:0xf bank_mask:0xf
	v_add_f32_dpp v12, v12, v12 row_mirror row_mask:0xf bank_mask:0xf
	v_add_f32_dpp v16, v16, v16 row_mirror row_mask:0xf bank_mask:0xf
	v_add_f32_dpp v20, v20, v20 row_mirror row_mask:0xf bank_mask:0xf
	v_add_f32_dpp v24, v24, v24 row_mirror row_mask:0xf bank_mask:0xf
	v_add_f32_dpp v28, v28, v28 row_mirror row_mask:0xf bank_mask:0xf
	v_add_f32_dpp v32, v32, v32 row_mirror row_mask:0xf bank_mask:0xf
	v_add_f32_dpp v36, v36, v36 row_mirror row_mask:0xf bank_mask:0xf
	v_add_f32_dpp v52, v52, v52 row_mirror row_mask:0xf bank_mask:0xf
	s_nop 1
	s_mov_b32 s82, 0x10001
	s_mov_b32 s83, 0x10001
	s_mov_b64 exec, s[82:83]
	ds_write_b32 v48, v112 offset:352
	v_max_f32_e32 v40, v40, v112
	ds_write_b32 v48, v4 offset:368
	v_max_f32_e32 v40, v40, v4
	ds_write_b32 v48, v8 offset:384
	v_max_f32_e32 v40, v40, v8
	ds_write_b32 v48, v12 offset:400
	v_max_f32_e32 v40, v40, v12
	ds_write_b32 v48, v16 offset:416
	v_max_f32_e32 v40, v40, v16
	ds_write_b32 v48, v20 offset:432
	v_max_f32_e32 v40, v40, v20
	ds_write_b32 v48, v24 offset:448
	v_max_f32_e32 v40, v40, v24
	ds_write_b32 v48, v28 offset:464
	v_max_f32_e32 v40, v40, v28
	ds_write_b32 v48, v32 offset:480
	v_max_f32_e32 v40, v40, v32
	ds_write_b32 v48, v36 offset:496
	v_max_f32_e32 v40, v40, v36
	s_mov_b64 exec, 1
	ds_write_b32 v48, v52 offset:512
	v_max_f32_e32 v40, v40, v52
	s_mov_b64 exec, -1
	s_nop 4
	global_load_dwordx4 v[112:115], v49, s[76:77]
	s_sub_u32 s76, s76, 0x10000
	s_subb_u32 s77, s77, 0
	global_load_dwordx4 v[4:7], v49, s[76:77]
	s_sub_u32 s76, s76, 0x10000
	s_subb_u32 s77, s77, 0
	global_load_dwordx4 v[8:11], v49, s[76:77]
	s_sub_u32 s76, s76, 0x10000
	s_subb_u32 s77, s77, 0
	global_load_dwordx4 v[12:15], v49, s[76:77]
	s_sub_u32 s76, s76, 0x10000
	s_subb_u32 s77, s77, 0
	global_load_dwordx4 v[16:19], v49, s[76:77]
	s_sub_u32 s76, s76, 0x10000
	s_subb_u32 s77, s77, 0
	global_load_dwordx4 v[20:23], v49, s[76:77]
	s_sub_u32 s76, s76, 0x10000
	s_subb_u32 s77, s77, 0
	global_load_dwordx4 v[24:27], v49, s[76:77]
	s_sub_u32 s76, s76, 0x10000
	s_subb_u32 s77, s77, 0
	global_load_dwordx4 v[28:31], v49, s[76:77]
	s_sub_u32 s76, s76, 0x10000
	s_subb_u32 s77, s77, 0
	global_load_dwordx4 v[32:35], v49, s[76:77]
	s_sub_u32 s76, s76, 0x10000
	s_subb_u32 s77, s77, 0
	global_load_dwordx4 v[36:39], v49, s[76:77]
	s_sub_u32 s76, s76, 0x10000
	s_subb_u32 s77, s77, 0
	global_load_dwordx4 v[52:55], v49, s[76:77]
	s_sub_u32 s76, s76, 0x10000
	s_subb_u32 s77, s77, 0
	s_waitcnt vmcnt(11)
	v_mul_f32_e32 v56, v56, v44
	v_mul_f32_e32 v60, v60, v44
	v_mul_f32_e32 v64, v64, v44
	v_mul_f32_e32 v68, v68, v44
	v_mul_f32_e32 v72, v72, v44
	v_mul_f32_e32 v76, v76, v44
	v_mul_f32_e32 v80, v80, v44
	v_mul_f32_e32 v84, v84, v44
	v_mul_f32_e32 v88, v88, v44
	v_mul_f32_e32 v92, v92, v44
	v_mul_f32_e32 v96, v96, v44
	v_fmac_f32_e32 v56, v57, v45
	v_fmac_f32_e32 v60, v61, v45
	v_fmac_f32_e32 v64, v65, v45
	v_fmac_f32_e32 v68, v69, v45
	v_fmac_f32_e32 v72, v73, v45
	v_fmac_f32_e32 v76, v77, v45
	v_fmac_f32_e32 v80, v81, v45
	v_fmac_f32_e32 v84, v85, v45
	v_fmac_f32_e32 v88, v89, v45
	v_fmac_f32_e32 v92, v93, v45
	v_fmac_f32_e32 v96, v97, v45
	v_fmac_f32_e32 v56, v58, v46
	v_fmac_f32_e32 v60, v62, v46
	v_fmac_f32_e32 v64, v66, v46
	v_fmac_f32_e32 v68, v70, v46
	v_fmac_f32_e32 v72, v74, v46
	v_fmac_f32_e32 v76, v78, v46
	v_fmac_f32_e32 v80, v82, v46
	v_fmac_f32_e32 v84, v86, v46
	v_fmac_f32_e32 v88, v90, v46
	v_fmac_f32_e32 v92, v94, v46
	v_fmac_f32_e32 v96, v98, v46
	v_fmac_f32_e32 v56, v59, v47
	v_fmac_f32_e32 v60, v63, v47
	v_fmac_f32_e32 v64, v67, v47
	v_fmac_f32_e32 v68, v71, v47
	v_fmac_f32_e32 v72, v75, v47
	v_fmac_f32_e32 v76, v79, v47
	v_fmac_f32_e32 v80, v83, v47
	v_fmac_f32_e32 v84, v87, v47
	v_fmac_f32_e32 v88, v91, v47
	v_fmac_f32_e32 v92, v95, v47
	v_fmac_f32_e32 v96, v99, v47
	s_nop 1
	v_add_f32_dpp v56, v56, v56 quad_perm:[1,0,3,2] row_mask:0xf bank_mask:0xf
	v_add_f32_dpp v60, v60, v60 quad_perm:[1,0,3,2] row_mask:0xf bank_mask:0xf
	v_add_f32_dpp v64, v64, v64 quad_perm:[1,0,3,2] row_mask:0xf bank_mask:0xf
	v_add_f32_dpp v68, v68, v68 quad_perm:[1,0,3,2] row_mask:0xf bank_mask:0xf
	v_add_f32_dpp v72, v72, v72 quad_perm:[1,0,3,2] row_mask:0xf bank_mask:0xf
	v_add_f32_dpp v76, v76, v76 quad_perm:[1,0,3,2] row_mask:0xf bank_mask:0xf
	v_add_f32_dpp v80, v80, v80 quad_perm:[1,0,3,2] row_mask:0xf bank_mask:0xf
	v_add_f32_dpp v84, v84, v84 quad_perm:[1,0,3,2] row_mask:0xf bank_mask:0xf
	v_add_f32_dpp v88, v88, v88 quad_perm:[1,0,3,2] row_mask:0xf bank_mask:0xf
; #define LAS __attribute__((address_space(3)))
; DI float bflo(unsigned w) { return __uint_as_float(w << 16); }
; DI float bfhi(unsigned w) { return __uint_as_float(w & 0xffff0000u); }
; DI void attn_sample_unit(const Params& p, int u, const bf16_t* Q, const bf16_t* Kb, const bf16_t* Vb, bf16_t* att, LAS float* sl, int lane) {
;     ...
;     for (int e = 0; e < 9; ++e) { const int pat = e / 3, r = e - 3 * pat; const int dil = 1 << (2 * pat);
;         const int j = lane + 64 * r; const bool valid = j <= 128; const int idx = 2048 + t - dil * (valid ? j : 0);
;         float dot = 0.f;
;         if (idx >= 2048) { const bf16_t* kp = Kb + ((size_t)NP + b * 4 + (idx - 2048)) * 1024 + h * 64;
; #pragma unroll
;             for (int d8 = 0; d8 < 8; ++d8) { const u32x4 kw = *(const u32x4*)(kp + 8 * d8); const f32x4 q0 = *(const LAS f32x4*)(sl + 8 * d8), q1 = *(const LAS f32x4*)(sl + 8 * d8 + 4);
;                 dot += (bflo(kw.x) * q0[0] + bfhi(kw.x) * q0[1]) + (bflo(kw.y) * q0[2] + bfhi(kw.y) * q0[3]) + (bflo(kw.z) * q1[0] + bfhi(kw.z) * q1[1]) + (bflo(kw.w) * q1[2] + bfhi(kw.w) * q1[3]); } }
;         else { const float* kp = ck + (((size_t)b * 2048 + idx) * 16 + h) * 64;
; #pragma unroll
;             for (int d4 = 0; d4 < 16; ++d4) { const f32x4 kv = *(const f32x4*)(kp + 4 * d4); const f32x4 qv = *(const LAS f32x4*)(sl + 4 * d4); dot += (kv[0] * qv[0] + kv[1] * qv[1]) + (kv[2] * qv[2] + kv[3] * qv[3]); } }
;         if (valid) { sl[64 + pat * 192 + j] = dot; mx = fmaxf(mx, dot); } }
	v_add_f32_dpp v92, v92, v92 quad_perm:[1,0,3,2] row_mask:0xf bank_mask:0xf
	v_add_f32_dpp v96, v96, v96 quad_perm:[1,0,3,2] row_mask:0xf bank_mask:0xf
	s_nop 1
	v_add_f32_dpp v56, v56, v56 quad_perm:[2,3,0,1] row_mask:0xf bank_mask:0xf
	v_add_f32_dpp v60, v60, v60 quad_perm:[2,3,0,1] row_mask:0xf bank_mask:0xf
	v_add_f32_dpp v64, v64, v64 quad_perm:[2,3,0,1] row_mask:0xf bank_mask:0xf
	v_add_f32_dpp v68, v68, v68 quad_perm:[2,3,0,1] row_mask:0xf bank_mask:0xf
	v_add_f32_dpp v72, v72, v72 quad_perm:[2,3,0,1] row_mask:0xf bank_mask:0xf
	v_add_f32_dpp v76, v76, v76 quad_perm:[2,3,0,1] row_mask:0xf bank_mask:0xf
	v_add_f32_dpp v80, v80, v80 quad_perm:[2,3,0,1] row_mask:0xf bank_mask:0xf
	v_add_f32_dpp v84, v84, v84 quad_perm:[2,3,0,1] row_mask:0xf bank_mask:0xf
	v_add_f32_dpp v88, v88, v88 quad_perm:[2,3,0,1] row_mask:0xf bank_mask:0xf
	v_add_f32_dpp v92, v92, v92 quad_perm:[2,3,0,1] row_mask:0xf bank_mask:0xf
	v_add_f32_dpp v96, v96, v96 quad_perm:[2,3,0,1] row_mask:0xf bank_mask:0xf
	s_nop 1
	v_add_f32_dpp v56, v56, v56 row_half_mirror row_mask:0xf bank_mask:0xf
	v_add_f32_dpp v60, v60, v60 row_half_mirror row_mask:0xf bank_mask:0xf
	v_add_f32_dpp v64, v64, v64 row_half_mirror row_mask:0xf bank_mask:0xf
	v_add_f32_dpp v68, v68, v68 row_half_mirror row_mask:0xf bank_mask:0xf
	v_add_f32_dpp v72, v72, v72 row_half_mirror row_mask:0xf bank_mask:0xf
	v_add_f32_dpp v76, v76, v76 row_half_mirror row_mask:0xf bank_mask:0xf
	v_add_f32_dpp v80, v80, v80 row_half_mirror row_mask:0xf bank_mask:0xf
	v_add_f32_dpp v84, v84, v84 row_half_mirror row_mask:0xf bank_mask:0xf
	v_add_f32_dpp v88, v88, v88 row_half_mirror row_mask:0xf bank_mask:0xf
	v_add_f32_dpp v92, v92, v92 row_half_mirror row_mask:0xf bank_mask:0xf
	v_add_f32_dpp v96, v96, v96 row_half_mirror row_mask:0xf bank_mask:0xf
	s_nop 1
	v_add_f32_dpp v56, v56, v56 row_mirror row_mask:0xf bank_mask:0xf
	v_add_f32_dpp v60, v60, v60 row_mirror row_mask:0xf bank_mask:0xf
	v_add_f32_dpp v64, v64, v64 row_mirror row_mask:0xf bank_mask:0xf
	v_add_f32_dpp v68, v68, v68 row_mirror row_mask:0xf bank_mask:0xf
	v_add_f32_dpp v72, v72, v72 row_mirror row_mask:0xf bank_mask:0xf
	v_add_f32_dpp v76, v76, v76 row_mirror row_mask:0xf bank_mask:0xf
	v_add_f32_dpp v80, v80, v80 row_mirror row_mask:0xf bank_mask:0xf
	v_add_f32_dpp v84, v84, v84 row_mirror row_mask:0xf bank_mask:0xf
	v_add_f32_dpp v88, v88, v88 row_mirror row_mask:0xf bank_mask:0xf
	v_add_f32_dpp v92, v92, v92 row_mirror row_mask:0xf bank_mask:0xf
	v_add_f32_dpp v96, v96, v96 row_mirror row_mask:0xf bank_mask:0xf
	s_nop 1
	s_mov_b32 s82, 0x10000
	s_mov_b32 s83, 0x10001
	s_mov_b64 exec, s[82:83]
	ds_write_b32 v48, v56 offset:768
	v_max_f32_e32 v40, v40, v56
	s_mov_b32 s82, 0x10001
	s_mov_b32 s83, 0x10001
	s_mov_b64 exec, s[82:83]
	ds_write_b32 v48, v60 offset:784
	v_max_f32_e32 v40, v40, v60
	ds_write_b32 v48, v64 offset:800
	v_max_f32_e32 v40, v40, v64
	ds_write_b32 v48, v68 offset:816
	v_max_f32_e32 v40, v40, v68
	ds_write_b32 v48, v72 offset:832
	v_max_f32_e32 v40, v40, v72
	ds_write_b32 v48, v76 offset:848
	v_max_f32_e32 v40, v40, v76
	ds_write_b32 v48, v80 offset:864
	v_max_f32_e32 v40, v40, v80
	ds_write_b32 v48, v84 offset:880
	v_max_f32_e32 v40, v40, v84
	ds_write_b32 v48, v88 offset:896
	v_max_f32_e32 v40, v40, v88
	ds_write_b32 v48, v92 offset:912
	v_max_f32_e32 v40, v40, v92
	ds_write_b32 v48, v96 offset:928
	v_max_f32_e32 v40, v40, v96
	s_mov_b64 exec, -1
	s_nop 4
	global_load_dwordx4 v[56:59], v49, s[76:77]
	s_sub_u32 s76, s76, 0x10000
	s_subb_u32 s77, s77, 0
	global_load_dwordx4 v[60:63], v49, s[76:77]
	s_sub_u32 s76, s76, 0x10000
	s_subb_u32 s77, s77, 0
	global_load_dwordx4 v[64:67], v49, s[76:77]
	s_sub_u32 s76, s76, 0x10000
	s_subb_u32 s77, s77, 0
	global_load_dwordx4 v[68:71], v49, s[76:77]
	s_sub_u32 s76, s76, 0x10000
	s_subb_u32 s77, s77, 0
	global_load_dwordx4 v[72:75], v49, s[76:77]
	s_sub_u32 s76, s76, 0x10000
	s_subb_u32 s77, s77, 0
	global_load_dwordx4 v[76:79], v49, s[76:77]
	s_sub_u32 s76, s76, 0x10000
	s_subb_u32 s77, s77, 0
	global_load_dwordx4 v[80:83], v49, s[76:77]
	s_sub_u32 s76, s76, 0x10000
	s_subb_u32 s77, s77, 0
	global_load_dwordx4 v[84:87], v49, s[76:77]
	s_sub_u32 s76, s76, 0x10000
	s_subb_u32 s77, s77, 0
	global_load_dwordx4 v[88:91], v49, s[76:77]
	s_sub_u32 s76, s76, 0x10000
	s_subb_u32 s77, s77, 0
	global_load_dwordx4 v[92:95], v49, s[76:77]
	s_sub_u32 s76, s76, 0x10000
	s_subb_u32 s77, s77, 0
	s_mov_b64 exec, 0xffff
	global_load_dwordx4 v[96:99], v49, s[76:77]
	s_mov_b64 exec, -1
	s_waitcnt vmcnt(11)
; #define LAS __attribute__((address_space(3)))
; DI float bflo(unsigned w) { return __uint_as_float(w << 16); }
; DI float bfhi(unsigned w) { return __uint_as_float(w & 0xffff0000u); }
; DI void attn_sample_unit(const Params& p, int u, const bf16_t* Q, const bf16_t* Kb, const bf16_t* Vb, bf16_t* att, LAS float* sl, int lane) {
;     ...
;     for (int e = 0; e < 9; ++e) { const int pat = e / 3, r = e - 3 * pat; const int dil = 1 << (2 * pat);
;         const int j = lane + 64 * r; const bool valid = j <= 128; const int idx = 2048 + t - dil * (valid ? j : 0);
;         float dot = 0.f;
;         if (idx >= 2048) { const bf16_t* kp = Kb + ((size_t)NP + b * 4 + (idx - 2048)) * 1024 + h * 64;
; #pragma unroll
;             for (int d8 = 0; d8 < 8; ++d8) { const u32x4 kw = *(const u32x4*)(kp + 8 * d8); const f32x4 q0 = *(const LAS f32x4*)(sl + 8 * d8), q1 = *(const LAS f32x4*)(sl + 8 * d8 + 4);
;                 dot += (bflo(kw.x) * q0[0] + bfhi(kw.x) * q0[1]) + (bflo(kw.y) * q0[2] + bfhi(kw.y) * q0[3]) + (bflo(kw.z) * q1[0] + bfhi(kw.z) * q1[1]) + (bflo(kw.w) * q1[2] + bfhi(kw.w) * q1[3]); } }
;         else { const float* kp = ck + (((size_t)b * 2048 + idx) * 16 + h) * 64;
; #pragma unroll
;             for (int d4 = 0; d4 < 16; ++d4) { const f32x4 kv = *(const f32x4*)(kp + 4 * d4); const f32x4 qv = *(const LAS f32x4*)(sl + 4 * d4); dot += (kv[0] * qv[0] + kv[1] * qv[1]) + (kv[2] * qv[2] + kv[3] * qv[3]); } }
;         if (valid) { sl[64 + pat * 192 + j] = dot; mx = fmaxf(mx, dot); } }
	v_mul_f32_e32 v112, v112, v44
	v_mul_f32_e32 v4, v4, v44
	v_mul_f32_e32 v8, v8, v44
	v_mul_f32_e32 v12, v12, v44
	v_mul_f32_e32 v16, v16, v44
	v_mul_f32_e32 v20, v20, v44
	v_mul_f32_e32 v24, v24, v44
	v_mul_f32_e32 v28, v28, v44
	v_mul_f32_e32 v32, v32, v44
	v_mul_f32_e32 v36, v36, v44
	v_mul_f32_e32 v52, v52, v44
	v_fmac_f32_e32 v112, v113, v45
	v_fmac_f32_e32 v4, v5, v45
	v_fmac_f32_e32 v8, v9, v45
	v_fmac_f32_e32 v12, v13, v45
	v_fmac_f32_e32 v16, v17, v45
	v_fmac_f32_e32 v20, v21, v45
	v_fmac_f32_e32 v24, v25, v45
	v_fmac_f32_e32 v28, v29, v45
	v_fmac_f32_e32 v32, v33, v45
	v_fmac_f32_e32 v36, v37, v45
	v_fmac_f32_e32 v52, v53, v45
	v_fmac_f32_e32 v112, v114, v46
	v_fmac_f32_e32 v4, v6, v46
	v_fmac_f32_e32 v8, v10, v46
	v_fmac_f32_e32 v12, v14, v46
	v_fmac_f32_e32 v16, v18, v46
	v_fmac_f32_e32 v20, v22, v46
	v_fmac_f32_e32 v24, v26, v46
	v_fmac_f32_e32 v28, v30, v46
	v_fmac_f32_e32 v32, v34, v46
	v_fmac_f32_e32 v36, v38, v46
	v_fmac_f32_e32 v52, v54, v46
	v_fmac_f32_e32 v112, v115, v47
	v_fmac_f32_e32 v4, v7, v47
	v_fmac_f32_e32 v8, v11, v47
	v_fmac_f32_e32 v12, v15, v47
	v_fmac_f32_e32 v16, v19, v47
	v_fmac_f32_e32 v20, v23, v47
	v_fmac_f32_e32 v24, v27, v47
	v_fmac_f32_e32 v28, v31, v47
	v_fmac_f32_e32 v32, v35, v47
	v_fmac_f32_e32 v36, v39, v47
	v_fmac_f32_e32 v52, v55, v47
	s_nop 1
	v_add_f32_dpp v112, v112, v112 quad_perm:[1,0,3,2] row_mask:0xf bank_mask:0xf
	v_add_f32_dpp v4, v4, v4 quad_perm:[1,0,3,2] row_mask:0xf bank_mask:0xf
	v_add_f32_dpp v8, v8, v8 quad_perm:[1,0,3,2] row_mask:0xf bank_mask:0xf
	v_add_f32_dpp v12, v12, v12 quad_perm:[1,0,3,2] row_mask:0xf bank_mask:0xf
	v_add_f32_dpp v16, v16, v16 quad_perm:[1,0,3,2] row_mask:0xf bank_mask:0xf
	v_add_f32_dpp v20, v20, v20 quad_perm:[1,0,3,2] row_mask:0xf bank_mask:0xf
	v_add_f32_dpp v24, v24, v24 quad_perm:[1,0,3,2] row_mask:0xf bank_mask:0xf
	v_add_f32_dpp v28, v28, v28 quad_perm:[1,0,3,2] row_mask:0xf bank_mask:0xf
	v_add_f32_dpp v32, v32, v32 quad_perm:[1,0,3,2] row_mask:0xf bank_mask:0xf
	v_add_f32_dpp v36, v36, v36 quad_perm:[1,0,3,2] row_mask:0xf bank_mask:0xf
	v_add_f32_dpp v52, v52, v52 quad_perm:[1,0,3,2] row_mask:0xf bank_mask:0xf
	s_nop 1
	v_add_f32_dpp v112, v112, v112 quad_perm:[2,3,0,1] row_mask:0xf bank_mask:0xf
	v_add_f32_dpp v4, v4, v4 quad_perm:[2,3,0,1] row_mask:0xf bank_mask:0xf
	v_add_f32_dpp v8, v8, v8 quad_perm:[2,3,0,1] row_mask:0xf bank_mask:0xf
	v_add_f32_dpp v12, v12, v12 quad_perm:[2,3,0,1] row_mask:0xf bank_mask:0xf
	v_add_f32_dpp v16, v16, v16 quad_perm:[2,3,0,1] row_mask:0xf bank_mask:0xf
	v_add_f32_dpp v20, v20, v20 quad_perm:[2,3,0,1] row_mask:0xf bank_mask:0xf
	v_add_f32_dpp v24, v24, v24 quad_perm:[2,3,0,1] row_mask:0xf bank_mask:0xf
	v_add_f32_dpp v28, v28, v28 quad_perm:[2,3,0,1] row_mask:0xf bank_mask:0xf
	v_add_f32_dpp v32, v32, v32 quad_perm:[2,3,0,1] row_mask:0xf bank_mask:0xf
	v_add_f32_dpp v36, v36, v36 quad_perm:[2,3,0,1] row_mask:0xf bank_mask:0xf
	v_add_f32_dpp v52, v52, v52 quad_perm:[2,3,0,1] row_mask:0xf bank_mask:0xf
	s_nop 1
	v_add_f32_dpp v112, v112, v112 row_half_mirror row_mask:0xf bank_mask:0xf
	v_add_f32_dpp v4, v4, v4 row_half_mirror row_mask:0xf bank_mask:0xf
	v_add_f32_dpp v8, v8, v8 row_half_mirror row_mask:0xf bank_mask:0xf
	v_add_f32_dpp v12, v12, v12 row_half_mirror row_mask:0xf bank_mask:0xf
	v_add_f32_dpp v16, v16, v16 row_half_mirror row_mask:0xf bank_mask:0xf
	v_add_f32_dpp v20, v20, v20 row_half_mirror row_mask:0xf bank_mask:0xf
	v_add_f32_dpp v24, v24, v24 row_half_mirror row_mask:0xf bank_mask:0xf
	v_add_f32_dpp v28, v28, v28 row_half_mirror row_mask:0xf bank_mask:0xf
	v_add_f32_dpp v32, v32, v32 row_half_mirror row_mask:0xf bank_mask:0xf
	v_add_f32_dpp v36, v36, v36 row_half_mirror row_mask:0xf bank_mask:0xf
	v_add_f32_dpp v52, v52, v52 row_half_mirror row_mask:0xf bank_mask:0xf
	s_nop 1
	v_add_f32_dpp v112, v112, v112 row_mirror row_mask:0xf bank_mask:0xf
	v_add_f32_dpp v4, v4, v4 row_mirror row_mask:0xf bank_mask:0xf
	v_add_f32_dpp v8, v8, v8 row_mirror row_mask:0xf bank_mask:0xf
	v_add_f32_dpp v12, v12, v12 row_mirror row_mask:0xf bank_mask:0xf
	v_add_f32_dpp v16, v16, v16 row_mirror row_mask:0xf bank_mask:0xf
	v_add_f32_dpp v20, v20, v20 row_mirror row_mask:0xf bank_mask:0xf
	v_add_f32_dpp v24, v24, v24 row_mirror row_mask:0xf bank_mask:0xf
	v_add_f32_dpp v28, v28, v28 row_mirror row_mask:0xf bank_mask:0xf
	v_add_f32_dpp v32, v32, v32 row_mirror row_mask:0xf bank_mask:0xf
	v_add_f32_dpp v36, v36, v36 row_mirror row_mask:0xf bank_mask:0xf
	v_add_f32_dpp v52, v52, v52 row_mirror row_mask:0xf bank_mask:0xf
	s_nop 1
	s_mov_b32 s82, 0x10001
	s_mov_b32 s83, 0x10001
	s_mov_b64 exec, s[82:83]
	ds_write_b32 v48, v112 offset:944
	v_max_f32_e32 v40, v40, v112
	ds_write_b32 v48, v4 offset:960
	v_max_f32_e32 v40, v40, v4
	ds_write_b32 v48, v8 offset:976
	v_max_f32_e32 v40, v40, v8
	ds_write_b32 v48, v12 offset:992
	v_max_f32_e32 v40, v40, v12
	ds_write_b32 v48, v16 offset:1008
	v_max_f32_e32 v40, v40, v16
	ds_write_b32 v48, v20 offset:1024
	v_max_f32_e32 v40, v40, v20
	ds_write_b32 v48, v24 offset:1040
	v_max_f32_e32 v40, v40, v24
	ds_write_b32 v48, v28 offset:1056
	v_max_f32_e32 v40, v40, v28
	ds_write_b32 v48, v32 offset:1072
	v_max_f32_e32 v40, v40, v32
	ds_write_b32 v48, v36 offset:1088
	v_max_f32_e32 v40, v40, v36
	ds_write_b32 v48, v52 offset:1104
	v_max_f32_e32 v40, v40, v52
	s_mov_b64 exec, -1
	s_nop 4
	v_lshlrev_b32_e32 v49, 4, v41
	v_sub_u32_e32 v49, s2, v49
	v_min_i32_e32 v50, 0x7ff, v49
	v_lshl_add_u32 v49, v49, 12, v43
	v_lshl_add_u32 v50, v50, 12, v43
	s_mov_b64 s[76:77], s[84:85]
	global_load_dwordx4 v[112:115], v50, s[76:77]
	s_sub_u32 s76, s76, 0x40000
	s_subb_u32 s77, s77, 0
	global_load_dwordx4 v[4:7], v49, s[76:77]
	s_sub_u32 s76, s76, 0x40000
	s_subb_u32 s77, s77, 0
	global_load_dwordx4 v[8:11], v49, s[76:77]
	s_sub_u32 s76, s76, 0x40000
	s_subb_u32 s77, s77, 0
	global_load_dwordx4 v[12:15], v49, s[76:77]
	s_sub_u32 s76, s76, 0x40000
	s_subb_u32 s77, s77, 0
	global_load_dwordx4 v[16:19], v49, s[76:77]
	s_sub_u32 s76, s76, 0x40000
	s_subb_u32 s77, s77, 0
	global_load_dwordx4 v[20:23], v49, s[76:77]
	s_sub_u32 s76, s76, 0x40000
	s_subb_u32 s77, s77, 0
	global_load_dwordx4 v[24:27], v49, s[76:77]
	s_sub_u32 s76, s76, 0x40000
	s_subb_u32 s77, s77, 0
	global_load_dwordx4 v[28:31], v49, s[76:77]
	s_sub_u32 s76, s76, 0x40000
	s_subb_u32 s77, s77, 0
	global_load_dwordx4 v[32:35], v49, s[76:77]
	s_sub_u32 s76, s76, 0x40000
	s_subb_u32 s77, s77, 0
	global_load_dwordx4 v[36:39], v49, s[76:77]
	s_sub_u32 s76, s76, 0x40000
	s_subb_u32 s77, s77, 0
	global_load_dwordx4 v[52:55], v49, s[76:77]
	s_sub_u32 s76, s76, 0x40000
	s_subb_u32 s77, s77, 0
	s_waitcnt vmcnt(11)
; #define LAS __attribute__((address_space(3)))
; DI float bflo(unsigned w) { return __uint_as_float(w << 16); }
; DI float bfhi(unsigned w) { return __uint_as_float(w & 0xffff0000u); }
; DI void attn_sample_unit(const Params& p, int u, const bf16_t* Q, const bf16_t* Kb, const bf16_t* Vb, bf16_t* att, LAS float* sl, int lane) {
;     ...
;     for (int e = 0; e < 9; ++e) { const int pat = e / 3, r = e - 3 * pat; const int dil = 1 << (2 * pat);
;         const int j = lane + 64 * r; const bool valid = j <= 128; const int idx = 2048 + t - dil * (valid ? j : 0);
;         float dot = 0.f;
;         if (idx >= 2048) { const bf16_t* kp = Kb + ((size_t)NP + b * 4 + (idx - 2048)) * 1024 + h * 64;
; #pragma unroll
;             for (int d8 = 0; d8 < 8; ++d8) { const u32x4 kw = *(const u32x4*)(kp + 8 * d8); const f32x4 q0 = *(const LAS f32x4*)(sl + 8 * d8), q1 = *(const LAS f32x4*)(sl + 8 * d8 + 4);
;                 dot += (bflo(kw.x) * q0[0] + bfhi(kw.x) * q0[1]) + (bflo(kw.y) * q0[2] + bfhi(kw.y) * q0[3]) + (bflo(kw.z) * q1[0] + bfhi(kw.z) * q1[1]) + (bflo(kw.w) * q1[2] + bfhi(kw.w) * q1[3]); } }
;         else { const float* kp = ck + (((size_t)b * 2048 + idx) * 16 + h) * 64;
; #pragma unroll
;             for (int d4 = 0; d4 < 16; ++d4) { const f32x4 kv = *(const f32x4*)(kp + 4 * d4); const f32x4 qv = *(const LAS f32x4*)(sl + 4 * d4); dot += (kv[0] * qv[0] + kv[1] * qv[1]) + (kv[2] * qv[2] + kv[3] * qv[3]); } }
;         if (valid) { sl[64 + pat * 192 + j] = dot; mx = fmaxf(mx, dot); } }
	v_mul_f32_e32 v56, v56, v44
	v_mul_f32_e32 v60, v60, v44
	v_mul_f32_e32 v64, v64, v44
	v_mul_f32_e32 v68, v68, v44
	v_mul_f32_e32 v72, v72, v44
	v_mul_f32_e32 v76, v76, v44
	v_mul_f32_e32 v80, v80, v44
	v_mul_f32_e32 v84, v84, v44
	v_mul_f32_e32 v88, v88, v44
	v_mul_f32_e32 v92, v92, v44
	v_mul_f32_e32 v96, v96, v44
	v_fmac_f32_e32 v56, v57, v45
	v_fmac_f32_e32 v60, v61, v45
	v_fmac_f32_e32 v64, v65, v45
	v_fmac_f32_e32 v68, v69, v45
	v_fmac_f32_e32 v72, v73, v45
	v_fmac_f32_e32 v76, v77, v45
	v_fmac_f32_e32 v80, v81, v45
	v_fmac_f32_e32 v84, v85, v45
	v_fmac_f32_e32 v88, v89, v45
	v_fmac_f32_e32 v92, v93, v45
	v_fmac_f32_e32 v96, v97, v45
	v_fmac_f32_e32 v56, v58, v46
	v_fmac_f32_e32 v60, v62, v46
	v_fmac_f32_e32 v64, v66, v46
	v_fmac_f32_e32 v68, v70, v46
	v_fmac_f32_e32 v72, v74, v46
	v_fmac_f32_e32 v76, v78, v46
	v_fmac_f32_e32 v80, v82, v46
	v_fmac_f32_e32 v84, v86, v46
	v_fmac_f32_e32 v88, v90, v46
	v_fmac_f32_e32 v92, v94, v46
	v_fmac_f32_e32 v96, v98, v46
	v_fmac_f32_e32 v56, v59, v47
	v_fmac_f32_e32 v60, v63, v47
	v_fmac_f32_e32 v64, v67, v47
	v_fmac_f32_e32 v68, v71, v47
	v_fmac_f32_e32 v72, v75, v47
	v_fmac_f32_e32 v76, v79, v47
	v_fmac_f32_e32 v80, v83, v47
	v_fmac_f32_e32 v84, v87, v47
	v_fmac_f32_e32 v88, v91, v47
	v_fmac_f32_e32 v92, v95, v47
	v_fmac_f32_e32 v96, v99, v47
	s_nop 1
	v_add_f32_dpp v56, v56, v56 quad_perm:[1,0,3,2] row_mask:0xf bank_mask:0xf
	v_add_f32_dpp v60, v60, v60 quad_perm:[1,0,3,2] row_mask:0xf bank_mask:0xf
	v_add_f32_dpp v64, v64, v64 quad_perm:[1,0,3,2] row_mask:0xf bank_mask:0xf
	v_add_f32_dpp v68, v68, v68 quad_perm:[1,0,3,2] row_mask:0xf bank_mask:0xf
	v_add_f32_dpp v72, v72, v72 quad_perm:[1,0,3,2] row_mask:0xf bank_mask:0xf
	v_add_f32_dpp v76, v76, v76 quad_perm:[1,0,3,2] row_mask:0xf bank_mask:0xf
	v_add_f32_dpp v80, v80, v80 quad_perm:[1,0,3,2] row_mask:0xf bank_mask:0xf
	v_add_f32_dpp v84, v84, v84 quad_perm:[1,0,3,2] row_mask:0xf bank_mask:0xf
	v_add_f32_dpp v88, v88, v88 quad_perm:[1,0,3,2] row_mask:0xf bank_mask:0xf
	v_add_f32_dpp v92, v92, v92 quad_perm:[1,0,3,2] row_mask:0xf bank_mask:0xf
	v_add_f32_dpp v96, v96, v96 quad_perm:[1,0,3,2] row_mask:0xf bank_mask:0xf
	s_nop 1
	v_add_f32_dpp v56, v56, v56 quad_perm:[2,3,0,1] row_mask:0xf bank_mask:0xf
	v_add_f32_dpp v60, v60, v60 quad_perm:[2,3,0,1] row_mask:0xf bank_mask:0xf
	v_add_f32_dpp v64, v64, v64 quad_perm:[2,3,0,1] row_mask:0xf bank_mask:0xf
	v_add_f32_dpp v68, v68, v68 quad_perm:[2,3,0,1] row_mask:0xf bank_mask:0xf
	v_add_f32_dpp v72, v72, v72 quad_perm:[2,3,0,1] row_mask:0xf bank_mask:0xf
	v_add_f32_dpp v76, v76, v76 quad_perm:[2,3,0,1] row_mask:0xf bank_mask:0xf
	v_add_f32_dpp v80, v80, v80 quad_perm:[2,3,0,1] row_mask:0xf bank_mask:0xf
	v_add_f32_dpp v84, v84, v84 quad_perm:[2,3,0,1] row_mask:0xf bank_mask:0xf
	v_add_f32_dpp v88, v88, v88 quad_perm:[2,3,0,1] row_mask:0xf bank_mask:0xf
	v_add_f32_dpp v92, v92, v92 quad_perm:[2,3,0,1] row_mask:0xf bank_mask:0xf
	v_add_f32_dpp v96, v96, v96 quad_perm:[2,3,0,1] row_mask:0xf bank_mask:0xf
	s_nop 1
	v_add_f32_dpp v56, v56, v56 row_half_mirror row_mask:0xf bank_mask:0xf
	v_add_f32_dpp v60, v60, v60 row_half_mirror row_mask:0xf bank_mask:0xf
	v_add_f32_dpp v64, v64, v64 row_half_mirror row_mask:0xf bank_mask:0xf
	v_add_f32_dpp v68, v68, v68 row_half_mirror row_mask:0xf bank_mask:0xf
	v_add_f32_dpp v72, v72, v72 row_half_mirror row_mask:0xf bank_mask:0xf
	v_add_f32_dpp v76, v76, v76 row_half_mirror row_mask:0xf bank_mask:0xf
	v_add_f32_dpp v80, v80, v80 row_half_mirror row_mask:0xf bank_mask:0xf
	v_add_f32_dpp v84, v84, v84 row_half_mirror row_mask:0xf bank_mask:0xf
	v_add_f32_dpp v88, v88, v88 row_half_mirror row_mask:0xf bank_mask:0xf
	v_add_f32_dpp v92, v92, v92 row_half_mirror row_mask:0xf bank_mask:0xf
	v_add_f32_dpp v96, v96, v96 row_half_mirror row_mask:0xf bank_mask:0xf
	s_nop 1
	v_add_f32_dpp v56, v56, v56 row_mirror row_mask:0xf bank_mask:0xf
	v_add_f32_dpp v60, v60, v60 row_mirror row_mask:0xf bank_mask:0xf
	v_add_f32_dpp v64, v64, v64 row_mirror row_mask:0xf bank_mask:0xf
	v_add_f32_dpp v68, v68, v68 row_mirror row_mask:0xf bank_mask:0xf
	v_add_f32_dpp v72, v72, v72 row_mirror row_mask:0xf bank_mask:0xf
	v_add_f32_dpp v76, v76, v76 row_mirror row_mask:0xf bank_mask:0xf
	v_add_f32_dpp v80, v80, v80 row_mirror row_mask:0xf bank_mask:0xf
	v_add_f32_dpp v84, v84, v84 row_mirror row_mask:0xf bank_mask:0xf
	v_add_f32_dpp v88, v88, v88 row_mirror row_mask:0xf bank_mask:0xf
	v_add_f32_dpp v92, v92, v92 row_mirror row_mask:0xf bank_mask:0xf
	v_add_f32_dpp v96, v96, v96 row_mirror row_mask:0xf bank_mask:0xf
	s_nop 1
	s_mov_b32 s82, 0x10001
	s_mov_b32 s83, 0x10001
	s_mov_b64 exec, s[82:83]
	ds_write_b32 v48, v56 offset:1120
	v_max_f32_e32 v40, v40, v56
	ds_write_b32 v48, v60 offset:1136
	v_max_f32_e32 v40, v40, v60
	ds_write_b32 v48, v64 offset:1152
	v_max_f32_e32 v40, v40, v64
	ds_write_b32 v48, v68 offset:1168
	v_max_f32_e32 v40, v40, v68
	ds_write_b32 v48, v72 offset:1184
	v_max_f32_e32 v40, v40, v72
	ds_write_b32 v48, v76 offset:1200
	v_max_f32_e32 v40, v40, v76
	ds_write_b32 v48, v80 offset:1216
	v_max_f32_e32 v40, v40, v80
	ds_write_b32 v48, v84 offset:1232
	v_max_f32_e32 v40, v40, v84
	ds_write_b32 v48, v88 offset:1248
	v_max_f32_e32 v40, v40, v88
	ds_write_b32 v48, v92 offset:1264
	v_max_f32_e32 v40, v40, v92
	s_mov_b64 exec, 1
	ds_write_b32 v48, v96 offset:1280
	v_max_f32_e32 v40, v40, v96
	s_mov_b64 exec, -1
	s_nop 4
	global_load_dwordx4 v[56:59], v49, s[76:77]
	s_sub_u32 s76, s76, 0x40000
	s_subb_u32 s77, s77, 0
	global_load_dwordx4 v[60:63], v49, s[76:77]
	s_sub_u32 s76, s76, 0x40000
	s_subb_u32 s77, s77, 0
	global_load_dwordx4 v[64:67], v49, s[76:77]
	s_sub_u32 s76, s76, 0x40000
	s_subb_u32 s77, s77, 0
	global_load_dwordx4 v[68:71], v49, s[76:77]
	s_sub_u32 s76, s76, 0x40000
	s_subb_u32 s77, s77, 0
	global_load_dwordx4 v[72:75], v49, s[76:77]
	s_sub_u32 s76, s76, 0x40000
	s_subb_u32 s77, s77, 0
	global_load_dwordx4 v[76:79], v49, s[76:77]
	s_sub_u32 s76, s76, 0x40000
	s_subb_u32 s77, s77, 0
	global_load_dwordx4 v[80:83], v49, s[76:77]
	s_sub_u32 s76, s76, 0x40000
	s_subb_u32 s77, s77, 0
	global_load_dwordx4 v[84:87], v49, s[76:77]
	s_sub_u32 s76, s76, 0x40000
	s_subb_u32 s77, s77, 0
	global_load_dwordx4 v[88:91], v49, s[76:77]
	s_sub_u32 s76, s76, 0x40000
	s_subb_u32 s77, s77, 0
	global_load_dwordx4 v[92:95], v49, s[76:77]
	s_sub_u32 s76, s76, 0x40000
	s_subb_u32 s77, s77, 0
	global_load_dwordx4 v[96:99], v49, s[76:77]
	s_sub_u32 s76, s76, 0x40000
	s_subb_u32 s77, s77, 0
	s_waitcnt vmcnt(11)
; #define LAS __attribute__((address_space(3)))
; DI float bflo(unsigned w) { return __uint_as_float(w << 16); }
; DI float bfhi(unsigned w) { return __uint_as_float(w & 0xffff0000u); }
; DI void attn_sample_unit(const Params& p, int u, const bf16_t* Q, const bf16_t* Kb, const bf16_t* Vb, bf16_t* att, LAS float* sl, int lane) {
;     ...
;     for (int e = 0; e < 9; ++e) { const int pat = e / 3, r = e - 3 * pat; const int dil = 1 << (2 * pat);
;         const int j = lane + 64 * r; const bool valid = j <= 128; const int idx = 2048 + t - dil * (valid ? j : 0);
;         float dot = 0.f;
;         if (idx >= 2048) { const bf16_t* kp = Kb + ((size_t)NP + b * 4 + (idx - 2048)) * 1024 + h * 64;
; #pragma unroll
;             for (int d8 = 0; d8 < 8; ++d8) { const u32x4 kw = *(const u32x4*)(kp + 8 * d8); const f32x4 q0 = *(const LAS f32x4*)(sl + 8 * d8), q1 = *(const LAS f32x4*)(sl + 8 * d8 + 4);
;                 dot += (bflo(kw.x) * q0[0] + bfhi(kw.x) * q0[1]) + (bflo(kw.y) * q0[2] + bfhi(kw.y) * q0[3]) + (bflo(kw.z) * q1[0] + bfhi(kw.z) * q1[1]) + (bflo(kw.w) * q1[2] + bfhi(kw.w) * q1[3]); } }
;         else { const float* kp = ck + (((size_t)b * 2048 + idx) * 16 + h) * 64;
; #pragma unroll
;             for (int d4 = 0; d4 < 16; ++d4) { const f32x4 kv = *(const f32x4*)(kp + 4 * d4); const f32x4 qv = *(const LAS f32x4*)(sl + 4 * d4); dot += (kv[0] * qv[0] + kv[1] * qv[1]) + (kv[2] * qv[2] + kv[3] * qv[3]); } }
;         if (valid) { sl[64 + pat * 192 + j] = dot; mx = fmaxf(mx, dot); } }
	v_mul_f32_e32 v112, v112, v44
	v_mul_f32_e32 v4, v4, v44
	v_mul_f32_e32 v8, v8, v44
	v_mul_f32_e32 v12, v12, v44
	v_mul_f32_e32 v16, v16, v44
	v_mul_f32_e32 v20, v20, v44
	v_mul_f32_e32 v24, v24, v44
	v_mul_f32_e32 v28, v28, v44
	v_mul_f32_e32 v32, v32, v44
	v_mul_f32_e32 v36, v36, v44
	v_mul_f32_e32 v52, v52, v44
	v_fmac_f32_e32 v112, v113, v45
	v_fmac_f32_e32 v4, v5, v45
	v_fmac_f32_e32 v8, v9, v45
	v_fmac_f32_e32 v12, v13, v45
	v_fmac_f32_e32 v16, v17, v45
	v_fmac_f32_e32 v20, v21, v45
	v_fmac_f32_e32 v24, v25, v45
	v_fmac_f32_e32 v28, v29, v45
	v_fmac_f32_e32 v32, v33, v45
	v_fmac_f32_e32 v36, v37, v45
	v_fmac_f32_e32 v52, v53, v45
	v_fmac_f32_e32 v112, v114, v46
	v_fmac_f32_e32 v4, v6, v46
	v_fmac_f32_e32 v8, v10, v46
	v_fmac_f32_e32 v12, v14, v46
	v_fmac_f32_e32 v16, v18, v46
	v_fmac_f32_e32 v20, v22, v46
	v_fmac_f32_e32 v24, v26, v46
	v_fmac_f32_e32 v28, v30, v46
	v_fmac_f32_e32 v32, v34, v46
	v_fmac_f32_e32 v36, v38, v46
	v_fmac_f32_e32 v52, v54, v46
	v_fmac_f32_e32 v112, v115, v47
	v_fmac_f32_e32 v4, v7, v47
	v_fmac_f32_e32 v8, v11, v47
	v_fmac_f32_e32 v12, v15, v47
	v_fmac_f32_e32 v16, v19, v47
	v_fmac_f32_e32 v20, v23, v47
	v_fmac_f32_e32 v24, v27, v47
	v_fmac_f32_e32 v28, v31, v47
	v_fmac_f32_e32 v32, v35, v47
	v_fmac_f32_e32 v36, v39, v47
	v_fmac_f32_e32 v52, v55, v47
	s_nop 1
	v_add_f32_dpp v112, v112, v112 quad_perm:[1,0,3,2] row_mask:0xf bank_mask:0xf
	v_add_f32_dpp v4, v4, v4 quad_perm:[1,0,3,2] row_mask:0xf bank_mask:0xf
	v_add_f32_dpp v8, v8, v8 quad_perm:[1,0,3,2] row_mask:0xf bank_mask:0xf
	v_add_f32_dpp v12, v12, v12 quad_perm:[1,0,3,2] row_mask:0xf bank_mask:0xf
	v_add_f32_dpp v16, v16, v16 quad_perm:[1,0,3,2] row_mask:0xf bank_mask:0xf
	v_add_f32_dpp v20, v20, v20 quad_perm:[1,0,3,2] row_mask:0xf bank_mask:0xf
	v_add_f32_dpp v24, v24, v24 quad_perm:[1,0,3,2] row_mask:0xf bank_mask:0xf
	v_add_f32_dpp v28, v28, v28 quad_perm:[1,0,3,2] row_mask:0xf bank_mask:0xf
	v_add_f32_dpp v32, v32, v32 quad_perm:[1,0,3,2] row_mask:0xf bank_mask:0xf
	v_add_f32_dpp v36, v36, v36 quad_perm:[1,0,3,2] row_mask:0xf bank_mask:0xf
	v_add_f32_dpp v52, v52, v52 quad_perm:[1,0,3,2] row_mask:0xf bank_mask:0xf
	s_nop 1
	v_add_f32_dpp v112, v112, v112 quad_perm:[2,3,0,1] row_mask:0xf bank_mask:0xf
	v_add_f32_dpp v4, v4, v4 quad_perm:[2,3,0,1] row_mask:0xf bank_mask:0xf
	v_add_f32_dpp v8, v8, v8 quad_perm:[2,3,0,1] row_mask:0xf bank_mask:0xf
	v_add_f32_dpp v12, v12, v12 quad_perm:[2,3,0,1] row_mask:0xf bank_mask:0xf
	v_add_f32_dpp v16, v16, v16 quad_perm:[2,3,0,1] row_mask:0xf bank_mask:0xf
	v_add_f32_dpp v20, v20, v20 quad_perm:[2,3,0,1] row_mask:0xf bank_mask:0xf
	v_add_f32_dpp v24, v24, v24 quad_perm:[2,3,0,1] row_mask:0xf bank_mask:0xf
	v_add_f32_dpp v28, v28, v28 quad_perm:[2,3,0,1] row_mask:0xf bank_mask:0xf
	v_add_f32_dpp v32, v32, v32 quad_perm:[2,3,0,1] row_mask:0xf bank_mask:0xf
	v_add_f32_dpp v36, v36, v36 quad_perm:[2,3,0,1] row_mask:0xf bank_mask:0xf
	v_add_f32_dpp v52, v52, v52 quad_perm:[2,3,0,1] row_mask:0xf bank_mask:0xf
	s_nop 1
	v_add_f32_dpp v112, v112, v112 row_half_mirror row_mask:0xf bank_mask:0xf
	v_add_f32_dpp v4, v4, v4 row_half_mirror row_mask:0xf bank_mask:0xf
	v_add_f32_dpp v8, v8, v8 row_half_mirror row_mask:0xf bank_mask:0xf
	v_add_f32_dpp v12, v12, v12 row_half_mirror row_mask:0xf bank_mask:0xf
	v_add_f32_dpp v16, v16, v16 row_half_mirror row_mask:0xf bank_mask:0xf
	v_add_f32_dpp v20, v20, v20 row_half_mirror row_mask:0xf bank_mask:0xf
	v_add_f32_dpp v24, v24, v24 row_half_mirror row_mask:0xf bank_mask:0xf
	v_add_f32_dpp v28, v28, v28 row_half_mirror row_mask:0xf bank_mask:0xf
	v_add_f32_dpp v32, v32, v32 row_half_mirror row_mask:0xf bank_mask:0xf
	v_add_f32_dpp v36, v36, v36 row_half_mirror row_mask:0xf bank_mask:0xf
	v_add_f32_dpp v52, v52, v52 row_half_mirror row_mask:0xf bank_mask:0xf
	s_nop 1
	v_add_f32_dpp v112, v112, v112 row_mirror row_mask:0xf bank_mask:0xf
	v_add_f32_dpp v4, v4, v4 row_mirror row_mask:0xf bank_mask:0xf
	v_add_f32_dpp v8, v8, v8 row_mirror row_mask:0xf bank_mask:0xf
	v_add_f32_dpp v12, v12, v12 row_mirror row_mask:0xf bank_mask:0xf
	v_add_f32_dpp v16, v16, v16 row_mirror row_mask:0xf bank_mask:0xf
	v_add_f32_dpp v20, v20, v20 row_mirror row_mask:0xf bank_mask:0xf
	v_add_f32_dpp v24, v24, v24 row_mirror row_mask:0xf bank_mask:0xf
	v_add_f32_dpp v28, v28, v28 row_mirror row_mask:0xf bank_mask:0xf
	v_add_f32_dpp v32, v32, v32 row_mirror row_mask:0xf bank_mask:0xf
	v_add_f32_dpp v36, v36, v36 row_mirror row_mask:0xf bank_mask:0xf
	v_add_f32_dpp v52, v52, v52 row_mirror row_mask:0xf bank_mask:0xf
	s_nop 1
	s_mov_b32 s82, 0x10000
	s_mov_b32 s83, 0x10001
	s_mov_b64 exec, s[82:83]
	ds_write_b32 v48, v112 offset:1536
	v_max_f32_e32 v40, v40, v112
	s_mov_b32 s82, 0x10001
	s_mov_b32 s83, 0x10001
	s_mov_b64 exec, s[82:83]
	ds_write_b32 v48, v4 offset:1552
	v_max_f32_e32 v40, v40, v4
	ds_write_b32 v48, v8 offset:1568
	v_max_f32_e32 v40, v40, v8
	ds_write_b32 v48, v12 offset:1584
	v_max_f32_e32 v40, v40, v12
	ds_write_b32 v48, v16 offset:1600
	v_max_f32_e32 v40, v40, v16
	ds_write_b32 v48, v20 offset:1616
	v_max_f32_e32 v40, v40, v20
	ds_write_b32 v48, v24 offset:1632
	v_max_f32_e32 v40, v40, v24
	ds_write_b32 v48, v28 offset:1648
	v_max_f32_e32 v40, v40, v28
	ds_write_b32 v48, v32 offset:1664
	v_max_f32_e32 v40, v40, v32
	ds_write_b32 v48, v36 offset:1680
	v_max_f32_e32 v40, v40, v36
	ds_write_b32 v48, v52 offset:1696
	v_max_f32_e32 v40, v40, v52
	s_mov_b64 exec, -1
	s_nop 4
	global_load_dwordx4 v[112:115], v49, s[76:77]
	s_sub_u32 s76, s76, 0x40000
	s_subb_u32 s77, s77, 0
	global_load_dwordx4 v[4:7], v49, s[76:77]
	s_sub_u32 s76, s76, 0x40000
	s_subb_u32 s77, s77, 0
	global_load_dwordx4 v[8:11], v49, s[76:77]
	s_sub_u32 s76, s76, 0x40000
	s_subb_u32 s77, s77, 0
	global_load_dwordx4 v[12:15], v49, s[76:77]
	s_sub_u32 s76, s76, 0x40000
	s_subb_u32 s77, s77, 0
	global_load_dwordx4 v[16:19], v49, s[76:77]
	s_sub_u32 s76, s76, 0x40000
	s_subb_u32 s77, s77, 0
	global_load_dwordx4 v[20:23], v49, s[76:77]
	s_sub_u32 s76, s76, 0x40000
	s_subb_u32 s77, s77, 0
	global_load_dwordx4 v[24:27], v49, s[76:77]
	s_sub_u32 s76, s76, 0x40000
	s_subb_u32 s77, s77, 0
	global_load_dwordx4 v[28:31], v49, s[76:77]
	s_sub_u32 s76, s76, 0x40000
	s_subb_u32 s77, s77, 0
	global_load_dwordx4 v[32:35], v49, s[76:77]
	s_sub_u32 s76, s76, 0x40000
	s_subb_u32 s77, s77, 0
	global_load_dwordx4 v[36:39], v49, s[76:77]
	s_sub_u32 s76, s76, 0x40000
	s_subb_u32 s77, s77, 0
	s_mov_b64 exec, 0xffff
	global_load_dwordx4 v[52:55], v49, s[76:77]
	s_mov_b64 exec, -1
	s_waitcnt vmcnt(11)
; #define LAS __attribute__((address_space(3)))
; DI float bflo(unsigned w) { return __uint_as_float(w << 16); }
; DI float bfhi(unsigned w) { return __uint_as_float(w & 0xffff0000u); }
; DI void attn_sample_unit(const Params& p, int u, const bf16_t* Q, const bf16_t* Kb, const bf16_t* Vb, bf16_t* att, LAS float* sl, int lane) {
;     ...
;     for (int e = 0; e < 9; ++e) { const int pat = e / 3, r = e - 3 * pat; const int dil = 1 << (2 * pat);
;         const int j = lane + 64 * r; const bool valid = j <= 128; const int idx = 2048 + t - dil * (valid ? j : 0);
;         float dot = 0.f;
;         if (idx >= 2048) { const bf16_t* kp = Kb + ((size_t)NP + b * 4 + (idx - 2048)) * 1024 + h * 64;
; #pragma unroll
;             for (int d8 = 0; d8 < 8; ++d8) { const u32x4 kw = *(const u32x4*)(kp + 8 * d8); const f32x4 q0 = *(const LAS f32x4*)(sl + 8 * d8), q1 = *(const LAS f32x4*)(sl + 8 * d8 + 4);
;                 dot += (bflo(kw.x) * q0[0] + bfhi(kw.x) * q0[1]) + (bflo(kw.y) * q0[2] + bfhi(kw.y) * q0[3]) + (bflo(kw.z) * q1[0] + bfhi(kw.z) * q1[1]) + (bflo(kw.w) * q1[2] + bfhi(kw.w) * q1[3]); } }
;         else { const float* kp = ck + (((size_t)b * 2048 + idx) * 16 + h) * 64;
; #pragma unroll
;             for (int d4 = 0; d4 < 16; ++d4) { const f32x4 kv = *(const f32x4*)(kp + 4 * d4); const f32x4 qv = *(const LAS f32x4*)(sl + 4 * d4); dot += (kv[0] * qv[0] + kv[1] * qv[1]) + (kv[2] * qv[2] + kv[3] * qv[3]); } }
;         if (valid) { sl[64 + pat * 192 + j] = dot; mx = fmaxf(mx, dot); } }
	v_mul_f32_e32 v56, v56, v44
	v_mul_f32_e32 v60, v60, v44
	v_mul_f32_e32 v64, v64, v44
	v_mul_f32_e32 v68, v68, v44
	v_mul_f32_e32 v72, v72, v44
	v_mul_f32_e32 v76, v76, v44
	v_mul_f32_e32 v80, v80, v44
	v_mul_f32_e32 v84, v84, v44
	v_mul_f32_e32 v88, v88, v44
	v_mul_f32_e32 v92, v92, v44
	v_mul_f32_e32 v96, v96, v44
	v_fmac_f32_e32 v56, v57, v45
	v_fmac_f32_e32 v60, v61, v45
	v_fmac_f32_e32 v64, v65, v45
	v_fmac_f32_e32 v68, v69, v45
	v_fmac_f32_e32 v72, v73, v45
	v_fmac_f32_e32 v76, v77, v45
	v_fmac_f32_e32 v80, v81, v45
	v_fmac_f32_e32 v84, v85, v45
	v_fmac_f32_e32 v88, v89, v45
	v_fmac_f32_e32 v92, v93, v45
	v_fmac_f32_e32 v96, v97, v45
	v_fmac_f32_e32 v56, v58, v46
	v_fmac_f32_e32 v60, v62, v46
	v_fmac_f32_e32 v64, v66, v46
	v_fmac_f32_e32 v68, v70, v46
	v_fmac_f32_e32 v72, v74, v46
	v_fmac_f32_e32 v76, v78, v46
	v_fmac_f32_e32 v80, v82, v46
	v_fmac_f32_e32 v84, v86, v46
	v_fmac_f32_e32 v88, v90, v46
	v_fmac_f32_e32 v92, v94, v46
	v_fmac_f32_e32 v96, v98, v46
	v_fmac_f32_e32 v56, v59, v47
	v_fmac_f32_e32 v60, v63, v47
	v_fmac_f32_e32 v64, v67, v47
	v_fmac_f32_e32 v68, v71, v47
	v_fmac_f32_e32 v72, v75, v47
	v_fmac_f32_e32 v76, v79, v47
	v_fmac_f32_e32 v80, v83, v47
	v_fmac_f32_e32 v84, v87, v47
	v_fmac_f32_e32 v88, v91, v47
	v_fmac_f32_e32 v92, v95, v47
	v_fmac_f32_e32 v96, v99, v47
	s_nop 1
	v_add_f32_dpp v56, v56, v56 quad_perm:[1,0,3,2] row_mask:0xf bank_mask:0xf
	v_add_f32_dpp v60, v60, v60 quad_perm:[1,0,3,2] row_mask:0xf bank_mask:0xf
	v_add_f32_dpp v64, v64, v64 quad_perm:[1,0,3,2] row_mask:0xf bank_mask:0xf
	v_add_f32_dpp v68, v68, v68 quad_perm:[1,0,3,2] row_mask:0xf bank_mask:0xf
	v_add_f32_dpp v72, v72, v72 quad_perm:[1,0,3,2] row_mask:0xf bank_mask:0xf
	v_add_f32_dpp v76, v76, v76 quad_perm:[1,0,3,2] row_mask:0xf bank_mask:0xf
	v_add_f32_dpp v80, v80, v80 quad_perm:[1,0,3,2] row_mask:0xf bank_mask:0xf
	v_add_f32_dpp v84, v84, v84 quad_perm:[1,0,3,2] row_mask:0xf bank_mask:0xf
	v_add_f32_dpp v88, v88, v88 quad_perm:[1,0,3,2] row_mask:0xf bank_mask:0xf
	v_add_f32_dpp v92, v92, v92 quad_perm:[1,0,3,2] row_mask:0xf bank_mask:0xf
	v_add_f32_dpp v96, v96, v96 quad_perm:[1,0,3,2] row_mask:0xf bank_mask:0xf
	s_nop 1
	v_add_f32_dpp v56, v56, v56 quad_perm:[2,3,0,1] row_mask:0xf bank_mask:0xf
	v_add_f32_dpp v60, v60, v60 quad_perm:[2,3,0,1] row_mask:0xf bank_mask:0xf
	v_add_f32_dpp v64, v64, v64 quad_perm:[2,3,0,1] row_mask:0xf bank_mask:0xf
	v_add_f32_dpp v68, v68, v68 quad_perm:[2,3,0,1] row_mask:0xf bank_mask:0xf
	v_add_f32_dpp v72, v72, v72 quad_perm:[2,3,0,1] row_mask:0xf bank_mask:0xf
	v_add_f32_dpp v76, v76, v76 quad_perm:[2,3,0,1] row_mask:0xf bank_mask:0xf
	v_add_f32_dpp v80, v80, v80 quad_perm:[2,3,0,1] row_mask:0xf bank_mask:0xf
	v_add_f32_dpp v84, v84, v84 quad_perm:[2,3,0,1] row_mask:0xf bank_mask:0xf
	v_add_f32_dpp v88, v88, v88 quad_perm:[2,3,0,1] row_mask:0xf bank_mask:0xf
	v_add_f32_dpp v92, v92, v92 quad_perm:[2,3,0,1] row_mask:0xf bank_mask:0xf
	v_add_f32_dpp v96, v96, v96 quad_perm:[2,3,0,1] row_mask:0xf bank_mask:0xf
	s_nop 1
	v_add_f32_dpp v56, v56, v56 row_half_mirror row_mask:0xf bank_mask:0xf
	v_add_f32_dpp v60, v60, v60 row_half_mirror row_mask:0xf bank_mask:0xf
	v_add_f32_dpp v64, v64, v64 row_half_mirror row_mask:0xf bank_mask:0xf
	v_add_f32_dpp v68, v68, v68 row_half_mirror row_mask:0xf bank_mask:0xf
	v_add_f32_dpp v72, v72, v72 row_half_mirror row_mask:0xf bank_mask:0xf
	v_add_f32_dpp v76, v76, v76 row_half_mirror row_mask:0xf bank_mask:0xf
	v_add_f32_dpp v80, v80, v80 row_half_mirror row_mask:0xf bank_mask:0xf
	v_add_f32_dpp v84, v84, v84 row_half_mirror row_mask:0xf bank_mask:0xf
	v_add_f32_dpp v88, v88, v88 row_half_mirror row_mask:0xf bank_mask:0xf
	v_add_f32_dpp v92, v92, v92 row_half_mirror row_mask:0xf bank_mask:0xf
	v_add_f32_dpp v96, v96, v96 row_half_mirror row_mask:0xf bank_mask:0xf
	s_nop 1
	v_add_f32_dpp v56, v56, v56 row_mirror row_mask:0xf bank_mask:0xf
	v_add_f32_dpp v60, v60, v60 row_mirror row_mask:0xf bank_mask:0xf
	v_add_f32_dpp v64, v64, v64 row_mirror row_mask:0xf bank_mask:0xf
	v_add_f32_dpp v68, v68, v68 row_mirror row_mask:0xf bank_mask:0xf
	v_add_f32_dpp v72, v72, v72 row_mirror row_mask:0xf bank_mask:0xf
	v_add_f32_dpp v76, v76, v76 row_mirror row_mask:0xf bank_mask:0xf
	v_add_f32_dpp v80, v80, v80 row_mirror row_mask:0xf bank_mask:0xf
	v_add_f32_dpp v84, v84, v84 row_mirror row_mask:0xf bank_mask:0xf
	v_add_f32_dpp v88, v88, v88 row_mirror row_mask:0xf bank_mask:0xf
	v_add_f32_dpp v92, v92, v92 row_mirror row_mask:0xf bank_mask:0xf
	v_add_f32_dpp v96, v96, v96 row_mirror row_mask:0xf bank_mask:0xf
	s_nop 1
	s_mov_b32 s82, 0x10001
	s_mov_b32 s83, 0x10001
	s_mov_b64 exec, s[82:83]
	ds_write_b32 v48, v56 offset:1712
	v_max_f32_e32 v40, v40, v56
	ds_write_b32 v48, v60 offset:1728
	v_max_f32_e32 v40, v40, v60
	ds_write_b32 v48, v64 offset:1744
	v_max_f32_e32 v40, v40, v64
	ds_write_b32 v48, v68 offset:1760
	v_max_f32_e32 v40, v40, v68
	ds_write_b32 v48, v72 offset:1776
	v_max_f32_e32 v40, v40, v72
	ds_write_b32 v48, v76 offset:1792
	v_max_f32_e32 v40, v40, v76
	ds_write_b32 v48, v80 offset:1808
	v_max_f32_e32 v40, v40, v80
	ds_write_b32 v48, v84 offset:1824
	v_max_f32_e32 v40, v40, v84
	ds_write_b32 v48, v88 offset:1840
	v_max_f32_e32 v40, v40, v88
	ds_write_b32 v48, v92 offset:1856
	v_max_f32_e32 v40, v40, v92
	ds_write_b32 v48, v96 offset:1872
	v_max_f32_e32 v40, v40, v96
	s_mov_b64 exec, -1
	s_nop 4
	s_waitcnt vmcnt(0)
; #define LAS __attribute__((address_space(3)))
; DI float bflo(unsigned w) { return __uint_as_float(w << 16); }
; DI float bfhi(unsigned w) { return __uint_as_float(w & 0xffff0000u); }
; DI void attn_sample_unit(const Params& p, int u, const bf16_t* Q, const bf16_t* Kb, const bf16_t* Vb, bf16_t* att, LAS float* sl, int lane) {
;     ...
;     for (int e = 0; e < 9; ++e) { const int pat = e / 3, r = e - 3 * pat; const int dil = 1 << (2 * pat);
;         const int j = lane + 64 * r; const bool valid = j <= 128; const int idx = 2048 + t - dil * (valid ? j : 0);
;         float dot = 0.f;
;         if (idx >= 2048) { const bf16_t* kp = Kb + ((size_t)NP + b * 4 + (idx - 2048)) * 1024 + h * 64;
; #pragma unroll
;             for (int d8 = 0; d8 < 8; ++d8) { const u32x4 kw = *(const u32x4*)(kp + 8 * d8); const f32x4 q0 = *(const LAS f32x4*)(sl + 8 * d8), q1 = *(const LAS f32x4*)(sl + 8 * d8 + 4);
;                 dot += (bflo(kw.x) * q0[0] + bfhi(kw.x) * q0[1]) + (bflo(kw.y) * q0[2] + bfhi(kw.y) * q0[3]) + (bflo(kw.z) * q1[0] + bfhi(kw.z) * q1[1]) + (bflo(kw.w) * q1[2] + bfhi(kw.w) * q1[3]); } }
;         else { const float* kp = ck + (((size_t)b * 2048 + idx) * 16 + h) * 64;
; #pragma unroll
;             for (int d4 = 0; d4 < 16; ++d4) { const f32x4 kv = *(const f32x4*)(kp + 4 * d4); const f32x4 qv = *(const LAS f32x4*)(sl + 4 * d4); dot += (kv[0] * qv[0] + kv[1] * qv[1]) + (kv[2] * qv[2] + kv[3] * qv[3]); } }
;         if (valid) { sl[64 + pat * 192 + j] = dot; mx = fmaxf(mx, dot); } }
;     mx = wave_max(mx);
	v_mul_f32_e32 v112, v112, v44
	v_mul_f32_e32 v4, v4, v44
	v_mul_f32_e32 v8, v8, v44
	v_mul_f32_e32 v12, v12, v44
	v_mul_f32_e32 v16, v16, v44
	v_mul_f32_e32 v20, v20, v44
	v_mul_f32_e32 v24, v24, v44
	v_mul_f32_e32 v28, v28, v44
	v_mul_f32_e32 v32, v32, v44
	v_mul_f32_e32 v36, v36, v44
	v_mul_f32_e32 v52, v52, v44
	v_fmac_f32_e32 v112, v113, v45
	v_fmac_f32_e32 v4, v5, v45
	v_fmac_f32_e32 v8, v9, v45
	v_fmac_f32_e32 v12, v13, v45
	v_fmac_f32_e32 v16, v17, v45
	v_fmac_f32_e32 v20, v21, v45
	v_fmac_f32_e32 v24, v25, v45
	v_fmac_f32_e32 v28, v29, v45
	v_fmac_f32_e32 v32, v33, v45
	v_fmac_f32_e32 v36, v37, v45
	v_fmac_f32_e32 v52, v53, v45
	v_fmac_f32_e32 v112, v114, v46
	v_fmac_f32_e32 v4, v6, v46
	v_fmac_f32_e32 v8, v10, v46
	v_fmac_f32_e32 v12, v14, v46
	v_fmac_f32_e32 v16, v18, v46
	v_fmac_f32_e32 v20, v22, v46
	v_fmac_f32_e32 v24, v26, v46
	v_fmac_f32_e32 v28, v30, v46
	v_fmac_f32_e32 v32, v34, v46
	v_fmac_f32_e32 v36, v38, v46
	v_fmac_f32_e32 v52, v54, v46
	v_fmac_f32_e32 v112, v115, v47
	v_fmac_f32_e32 v4, v7, v47
	v_fmac_f32_e32 v8, v11, v47
	v_fmac_f32_e32 v12, v15, v47
	v_fmac_f32_e32 v16, v19, v47
	v_fmac_f32_e32 v20, v23, v47
	v_fmac_f32_e32 v24, v27, v47
	v_fmac_f32_e32 v28, v31, v47
	v_fmac_f32_e32 v32, v35, v47
	v_fmac_f32_e32 v36, v39, v47
	v_fmac_f32_e32 v52, v55, v47
	s_nop 1
	v_add_f32_dpp v112, v112, v112 quad_perm:[1,0,3,2] row_mask:0xf bank_mask:0xf
	v_add_f32_dpp v4, v4, v4 quad_perm:[1,0,3,2] row_mask:0xf bank_mask:0xf
	v_add_f32_dpp v8, v8, v8 quad_perm:[1,0,3,2] row_mask:0xf bank_mask:0xf
	v_add_f32_dpp v12, v12, v12 quad_perm:[1,0,3,2] row_mask:0xf bank_mask:0xf
	v_add_f32_dpp v16, v16, v16 quad_perm:[1,0,3,2] row_mask:0xf bank_mask:0xf
	v_add_f32_dpp v20, v20, v20 quad_perm:[1,0,3,2] row_mask:0xf bank_mask:0xf
	v_add_f32_dpp v24, v24, v24 quad_perm:[1,0,3,2] row_mask:0xf bank_mask:0xf
	v_add_f32_dpp v28, v28, v28 quad_perm:[1,0,3,2] row_mask:0xf bank_mask:0xf
	v_add_f32_dpp v32, v32, v32 quad_perm:[1,0,3,2] row_mask:0xf bank_mask:0xf
	v_add_f32_dpp v36, v36, v36 quad_perm:[1,0,3,2] row_mask:0xf bank_mask:0xf
	v_add_f32_dpp v52, v52, v52 quad_perm:[1,0,3,2] row_mask:0xf bank_mask:0xf
	s_nop 1
	v_add_f32_dpp v112, v112, v112 quad_perm:[2,3,0,1] row_mask:0xf bank_mask:0xf
	v_add_f32_dpp v4, v4, v4 quad_perm:[2,3,0,1] row_mask:0xf bank_mask:0xf
	v_add_f32_dpp v8, v8, v8 quad_perm:[2,3,0,1] row_mask:0xf bank_mask:0xf
	v_add_f32_dpp v12, v12, v12 quad_perm:[2,3,0,1] row_mask:0xf bank_mask:0xf
	v_add_f32_dpp v16, v16, v16 quad_perm:[2,3,0,1] row_mask:0xf bank_mask:0xf
	v_add_f32_dpp v20, v20, v20 quad_perm:[2,3,0,1] row_mask:0xf bank_mask:0xf
	v_add_f32_dpp v24, v24, v24 quad_perm:[2,3,0,1] row_mask:0xf bank_mask:0xf
	v_add_f32_dpp v28, v28, v28 quad_perm:[2,3,0,1] row_mask:0xf bank_mask:0xf
	v_add_f32_dpp v32, v32, v32 quad_perm:[2,3,0,1] row_mask:0xf bank_mask:0xf
	v_add_f32_dpp v36, v36, v36 quad_perm:[2,3,0,1] row_mask:0xf bank_mask:0xf
	v_add_f32_dpp v52, v52, v52 quad_perm:[2,3,0,1] row_mask:0xf bank_mask:0xf
	s_nop 1
	v_add_f32_dpp v112, v112, v112 row_half_mirror row_mask:0xf bank_mask:0xf
	v_add_f32_dpp v4, v4, v4 row_half_mirror row_mask:0xf bank_mask:0xf
	v_add_f32_dpp v8, v8, v8 row_half_mirror row_mask:0xf bank_mask:0xf
	v_add_f32_dpp v12, v12, v12 row_half_mirror row_mask:0xf bank_mask:0xf
	v_add_f32_dpp v16, v16, v16 row_half_mirror row_mask:0xf bank_mask:0xf
	v_add_f32_dpp v20, v20, v20 row_half_mirror row_mask:0xf bank_mask:0xf
	v_add_f32_dpp v24, v24, v24 row_half_mirror row_mask:0xf bank_mask:0xf
	v_add_f32_dpp v28, v28, v28 row_half_mirror row_mask:0xf bank_mask:0xf
	v_add_f32_dpp v32, v32, v32 row_half_mirror row_mask:0xf bank_mask:0xf
	v_add_f32_dpp v36, v36, v36 row_half_mirror row_mask:0xf bank_mask:0xf
	v_add_f32_dpp v52, v52, v52 row_half_mirror row_mask:0xf bank_mask:0xf
	s_nop 1
	v_add_f32_dpp v112, v112, v112 row_mirror row_mask:0xf bank_mask:0xf
	v_add_f32_dpp v4, v4, v4 row_mirror row_mask:0xf bank_mask:0xf
	v_add_f32_dpp v8, v8, v8 row_mirror row_mask:0xf bank_mask:0xf
	v_add_f32_dpp v12, v12, v12 row_mirror row_mask:0xf bank_mask:0xf
	v_add_f32_dpp v16, v16, v16 row_mirror row_mask:0xf bank_mask:0xf
	v_add_f32_dpp v20, v20, v20 row_mirror row_mask:0xf bank_mask:0xf
	v_add_f32_dpp v24, v24, v24 row_mirror row_mask:0xf bank_mask:0xf
	v_add_f32_dpp v28, v28, v28 row_mirror row_mask:0xf bank_mask:0xf
	v_add_f32_dpp v32, v32, v32 row_mirror row_mask:0xf bank_mask:0xf
	v_add_f32_dpp v36, v36, v36 row_mirror row_mask:0xf bank_mask:0xf
	v_add_f32_dpp v52, v52, v52 row_mirror row_mask:0xf bank_mask:0xf
	s_nop 1
	s_mov_b32 s82, 0x10001
	s_mov_b32 s83, 0x10001
	s_mov_b64 exec, s[82:83]
	ds_write_b32 v48, v112 offset:1888
	v_max_f32_e32 v40, v40, v112
	ds_write_b32 v48, v4 offset:1904
	v_max_f32_e32 v40, v40, v4
	ds_write_b32 v48, v8 offset:1920
	v_max_f32_e32 v40, v40, v8
	ds_write_b32 v48, v12 offset:1936
	v_max_f32_e32 v40, v40, v12
	ds_write_b32 v48, v16 offset:1952
	v_max_f32_e32 v40, v40, v16
	ds_write_b32 v48, v20 offset:1968
	v_max_f32_e32 v40, v40, v20
	ds_write_b32 v48, v24 offset:1984
	v_max_f32_e32 v40, v40, v24
	ds_write_b32 v48, v28 offset:2000
	v_max_f32_e32 v40, v40, v28
	ds_write_b32 v48, v32 offset:2016
	v_max_f32_e32 v40, v40, v32
	ds_write_b32 v48, v36 offset:2032
	v_max_f32_e32 v40, v40, v36
	s_mov_b64 exec, 1
	ds_write_b32 v48, v52 offset:2048
	v_max_f32_e32 v40, v40, v52
	s_mov_b64 exec, -1
	s_nop 4
	s_waitcnt vmcnt(0) lgkmcnt(0)
